# GEMM tile epilogues: waves 0-3 run at s_setprio 1 (raised after their alignment barrier), reset to 0 at every K-loop iteration head; K-loops stay at equal priority
# speedup vs baseline: 1.0007x; 1.0007x over previous
; #define PG8_STAGE(bufoff, gbase, voff) do { _Pragma("unroll") for (int _i = 0; _i < 2; ++_i) \
;         __builtin_amdgcn_global_load_lds((const unsigned*)((const char*)(gbase) + (voff)[_i]), (LAS unsigned*)(lds + (bufoff) + ldsw + _i * 8192), 16, 0, 0); } while (0)
; #define PG8_LDA(dst, b, h) do { _Pragma("unroll") for (int m = 0; m < 4; ++m) _Pragma("unroll") for (int k = 0; k < 2; ++k) dst[m][k] = *(const LAS bf16x8*)(lds + PG8_SA(b, h) + aoff + m * 2048 + k * 1024); } while (0)
; #define PG8_LDB(dst, b, h) do { _Pragma("unroll") for (int n = 0; n < 2; ++n) _Pragma("unroll") for (int k = 0; k < 2; ++k) dst[n][k] = *(const LAS bf16x8*)(lds + PG8_SB(b, h) + boff + n * 2048 + k * 1024); } while (0)
; #define PG8_WAIT_V(n) asm volatile("s_waitcnt vmcnt(" #n ")" ::: "memory")
; #define PG8_WAIT_L(n) asm volatile("s_waitcnt lgkmcnt(" #n ")" ::: "memory")
; template <class Epi, bool ALIGN_EPI>
; __device__ __forceinline__ void gemm_phase(LAS unsigned char* lds, const int tid, const Gemm g, const StaticOrder& S, const Epi& E) {
;     ...
;     for (;;) {
;         const bool has_next = S.next(ui + 1, nxt);
;         const char* nA = has_next ? (const char*)g.A + (size_t)nxt.pm * tstepA + PG8_KOFFA(nxt) : cA; const char* nB = has_next ? (const char*)g.Bt + (size_t)nxt.pn * tstepB + PG8_KOFFB(nxt) : cB;
;         const int nt = cur.ks >= 0 ? nt_split : nt_full;
;         for (int t = 0; t < nt; t += 2) {
;             if constexpr (Epi::HOOK) { if (t != 0 && (t & 7) == 0) E.hook(acc, cur, (t >> 3) - 1, wr, wc, fr, fq); }
;             const bool last = (t == nt - 2);
;             const char* a1 = cA + (size_t)(t + 1) * kstepA;
;             const char* a2 = last ? nA : cA + (size_t)(t + 2) * kstepA; const char* b2 = last ? nB : cB + (size_t)(t + 2) * kstepB;
;             const char* a3 = a2 + kstepA; const char* b3 = b2 + kstepB;
;             PG8_LDB(B0, 0, 0); PG8_LDB(B1, 0, 1); PG8_SCHED; PG8_LDA(At, 0, 0); PG8_STAGE(PG8_SA(1, 1), a1 + hstepA, voffA);
;             PG8_WAIT_V(8); PG8_WAIT_L(0); PG8_BAR; PG8_MMA(0, 0, At, B0); PG8_MMA(0, 1, At, B1); PG8_BAR; PG8_SCHED;
;             PG8_LDA(At, 0, 1); PG8_STAGE(PG8_SB(0, 0), b2, voffB); PG8_STAGE(PG8_SB(0, 1), b2 + hstepB, voffB); PG8_STAGE(PG8_SA(0, 0), a2, voffA);
;             PG8_WAIT_V(8); PG8_WAIT_L(0); PG8_BAR; PG8_MMA(1, 0, At, B0); PG8_MMA(1, 1, At, B1); PG8_BAR; PG8_SCHED;
.LBB0_113:
	s_setprio 0
	s_add_i32 s90, s90, 2
	s_and_b64 s[34:35], exec, s[34:35]
	s_cselect_b32 s55, s23, s27
	s_cselect_b32 s54, s22, s25
	s_add_u32 s34, s92, 0x120000
	s_addc_u32 s35, s93, 0
	s_add_i32 s91, 0, 0x10000
	s_add_i32 s96, 0, 0x14000
	v_add_u32_e32 v148, s91, v175
	v_add_u32_e32 v164, s96, v175
	ds_read_b128 v[136:139], v148
	ds_read_b128 v[140:143], v148 offset:1024
	ds_read_b128 v[144:147], v148 offset:2048
	ds_read_b128 v[148:151], v148 offset:3072
	ds_read_b128 v[152:155], v164
	ds_read_b128 v[156:159], v164 offset:1024
	ds_read_b128 v[160:163], v164 offset:2048
	ds_read_b128 v[164:167], v164 offset:3072
	v_lshl_add_u64 v[172:173], s[30:31], 0, v[134:135]
	s_add_i32 m0, s56, 0xc000
	ds_read_b128 v[168:171], v177
	ds_read_b128 v[178:181], v177 offset:1024
	ds_read_b128 v[182:185], v177 offset:2048
	ds_read_b128 v[186:189], v177 offset:3072
	ds_read_b128 v[190:193], v177 offset:4096
	ds_read_b128 v[210:213], v177 offset:5120
	ds_read_b128 v[214:217], v177 offset:6144
	ds_read_b128 v[218:221], v177 offset:7168
	global_load_lds_dwordx4 v[172:173], off
	v_lshl_add_u64 v[172:173], s[30:31], 0, v[132:133]
	s_add_i32 m0, s56, 0xe000
	s_nop 0
	global_load_lds_dwordx4 v[172:173], off
	s_sub_u32 s98, s30, 0x4000
	s_subb_u32 s99, s31, 0
	v_lshl_add_u64 v[172:173], s[98:99], 0, v[134:135]
	s_mov_b32 m0, s70
	s_nop 0
	global_load_lds_dwordx4 v[172:173], off
	v_lshl_add_u64 v[172:173], s[98:99], 0, v[132:133]
	s_mov_b32 m0, s71
	s_nop 0
	global_load_lds_dwordx4 v[172:173], off
	s_waitcnt vmcnt(8)
	s_waitcnt lgkmcnt(0)
	s_barrier
	v_mfma_f32_16x16x32_bf16 v[126:129], v[136:139], v[168:171], v[126:129]
	v_mfma_f32_16x16x32_bf16 v[94:97], v[144:147], v[168:171], v[94:97]
	v_mfma_f32_16x16x32_bf16 v[122:125], v[136:139], v[182:185], v[122:125]
	v_mfma_f32_16x16x32_bf16 v[90:93], v[144:147], v[182:185], v[90:93]
	v_mfma_f32_16x16x32_bf16 v[118:121], v[136:139], v[190:193], v[118:121]
	v_mfma_f32_16x16x32_bf16 v[86:89], v[144:147], v[190:193], v[86:89]
	v_mfma_f32_16x16x32_bf16 v[114:117], v[136:139], v[214:217], v[114:117]
	v_mfma_f32_16x16x32_bf16 v[82:85], v[144:147], v[214:217], v[82:85]
	v_mfma_f32_16x16x32_bf16 v[126:129], v[140:143], v[178:181], v[126:129]
	v_mfma_f32_16x16x32_bf16 v[94:97], v[148:151], v[178:181], v[94:97]
	v_mfma_f32_16x16x32_bf16 v[122:125], v[140:143], v[186:189], v[122:125]
	v_mfma_f32_16x16x32_bf16 v[90:93], v[148:151], v[186:189], v[90:93]
	v_mfma_f32_16x16x32_bf16 v[118:121], v[140:143], v[210:213], v[118:121]
	v_mfma_f32_16x16x32_bf16 v[86:89], v[148:151], v[210:213], v[86:89]
	v_mfma_f32_16x16x32_bf16 v[114:117], v[140:143], v[218:221], v[114:117]
	v_mfma_f32_16x16x32_bf16 v[82:85], v[148:151], v[218:221], v[82:85]
	v_mfma_f32_16x16x32_bf16 v[62:65], v[152:155], v[168:171], v[62:65]
	v_mfma_f32_16x16x32_bf16 v[38:41], v[160:163], v[168:171], v[38:41]
	v_mfma_f32_16x16x32_bf16 v[58:61], v[152:155], v[182:185], v[58:61]
	v_mfma_f32_16x16x32_bf16 v[30:33], v[160:163], v[182:185], v[30:33]
	v_mfma_f32_16x16x32_bf16 v[54:57], v[152:155], v[190:193], v[54:57]
	v_mfma_f32_16x16x32_bf16 v[22:25], v[160:163], v[190:193], v[22:25]
	v_mfma_f32_16x16x32_bf16 v[50:53], v[152:155], v[214:217], v[50:53]
	v_mfma_f32_16x16x32_bf16 v[18:21], v[160:163], v[214:217], v[18:21]
	v_mfma_f32_16x16x32_bf16 v[62:65], v[156:159], v[178:181], v[62:65]
	v_mfma_f32_16x16x32_bf16 v[38:41], v[164:167], v[178:181], v[38:41]
	v_mfma_f32_16x16x32_bf16 v[58:61], v[156:159], v[186:189], v[58:61]
	v_mfma_f32_16x16x32_bf16 v[30:33], v[164:167], v[186:189], v[30:33]
	v_mfma_f32_16x16x32_bf16 v[54:57], v[156:159], v[210:213], v[54:57]
	v_mfma_f32_16x16x32_bf16 v[22:25], v[164:167], v[210:213], v[22:25]
	v_mfma_f32_16x16x32_bf16 v[50:53], v[156:159], v[218:221], v[50:53]
	v_mfma_f32_16x16x32_bf16 v[18:21], v[164:167], v[218:221], v[18:21]
	s_barrier
	s_add_i32 s91, s91, s29
	v_lshl_add_u64 v[172:173], s[54:55], 0, v[0:1]
	s_mov_b32 m0, s91
	ds_read_b128 v[168:171], v177 offset:16384
	ds_read_b128 v[178:181], v177 offset:17408
	ds_read_b128 v[182:185], v177 offset:18432
	ds_read_b128 v[186:189], v177 offset:19456
	ds_read_b128 v[190:193], v177 offset:20480
	ds_read_b128 v[210:213], v177 offset:21504
	ds_read_b128 v[214:217], v177 offset:22528
	ds_read_b128 v[218:221], v177 offset:23552
	global_load_lds_dwordx4 v[172:173], off
	s_add_i32 m0, s91, 0x2000
	s_add_u32 s94, s54, 0x4000
	v_lshl_add_u64 v[172:173], s[54:55], 0, v[130:131]
	s_addc_u32 s95, s55, 0
	s_add_i32 s91, s96, s29
	global_load_lds_dwordx4 v[172:173], off
	v_lshl_add_u64 v[172:173], s[94:95], 0, v[0:1]
	s_mov_b32 m0, s91
	s_nop 0
	global_load_lds_dwordx4 v[172:173], off
	v_lshl_add_u64 v[172:173], s[94:95], 0, v[130:131]
	s_add_i32 m0, s91, 0x2000
	s_nop 0
	global_load_lds_dwordx4 v[172:173], off
	s_waitcnt vmcnt(4)
	s_waitcnt lgkmcnt(0)
	s_barrier
; #define PG8_STAGE(bufoff, gbase, voff) do { _Pragma("unroll") for (int _i = 0; _i < 2; ++_i) \
;         __builtin_amdgcn_global_load_lds((const unsigned*)((const char*)(gbase) + (voff)[_i]), (LAS unsigned*)(lds + (bufoff) + ldsw + _i * 8192), 16, 0, 0); } while (0)
; #define PG8_LDA(dst, b, h) do { _Pragma("unroll") for (int m = 0; m < 4; ++m) _Pragma("unroll") for (int k = 0; k < 2; ++k) dst[m][k] = *(const LAS bf16x8*)(lds + PG8_SA(b, h) + aoff + m * 2048 + k * 1024); } while (0)
; #define PG8_LDB(dst, b, h) do { _Pragma("unroll") for (int n = 0; n < 2; ++n) _Pragma("unroll") for (int k = 0; k < 2; ++k) dst[n][k] = *(const LAS bf16x8*)(lds + PG8_SB(b, h) + boff + n * 2048 + k * 1024); } while (0)
; #define PG8_MMA(ai, bj, At, Bt) do { __builtin_amdgcn_s_setprio(1); _Pragma("unroll") for (int m = 0; m < 4; ++m) _Pragma("unroll") for (int n = 0; n < 2; ++n) _Pragma("unroll") for (int k = 0; k < 2; ++k) \
;         acc[ai][bj][m][n] = __builtin_amdgcn_mfma_f32_16x16x32_bf16(Bt[n][k], At[m][k], acc[ai][bj][m][n], 0, 0, 0); __builtin_amdgcn_s_setprio(0); } while (0)
; #define PG8_WAIT_V(n) asm volatile("s_waitcnt vmcnt(" #n ")" ::: "memory")
; #define PG8_WAIT_L(n) asm volatile("s_waitcnt lgkmcnt(" #n ")" ::: "memory")
; #define PG8_BAR __builtin_amdgcn_s_barrier()
; #define PG8_SCHED __builtin_amdgcn_sched_barrier(0)
; template <class Epi, bool ALIGN_EPI>
; __device__ __forceinline__ void gemm_phase(LAS unsigned char* lds, const int tid, const Gemm g, const StaticOrder& S, const Epi& E) {
;     ...
;             PG8_WAIT_V(8); PG8_WAIT_L(0); PG8_BAR; PG8_MMA(1, 0, At, B0); PG8_MMA(1, 1, At, B1); PG8_BAR; PG8_SCHED;
;             PG8_LDB(B0, 1, 0); PG8_LDB(B1, 1, 1); PG8_SCHED; PG8_LDA(At, 1, 0); PG8_STAGE(PG8_SA(0, 1), a2 + hstepA, voffA);
;             PG8_WAIT_V(8); PG8_WAIT_L(0); PG8_BAR; PG8_MMA(0, 0, At, B0); PG8_MMA(0, 1, At, B1); PG8_BAR; PG8_SCHED;
	v_mfma_f32_16x16x32_bf16 v[110:113], v[136:139], v[168:171], v[110:113]
	v_mfma_f32_16x16x32_bf16 v[78:81], v[144:147], v[168:171], v[78:81]
	v_mfma_f32_16x16x32_bf16 v[106:109], v[136:139], v[182:185], v[106:109]
	v_mfma_f32_16x16x32_bf16 v[74:77], v[144:147], v[182:185], v[74:77]
	v_mfma_f32_16x16x32_bf16 v[102:105], v[136:139], v[190:193], v[102:105]
	v_mfma_f32_16x16x32_bf16 v[70:73], v[144:147], v[190:193], v[70:73]
	v_mfma_f32_16x16x32_bf16 v[98:101], v[136:139], v[214:217], v[98:101]
	v_mfma_f32_16x16x32_bf16 v[66:69], v[144:147], v[214:217], v[66:69]
	v_mfma_f32_16x16x32_bf16 v[110:113], v[140:143], v[178:181], v[110:113]
	v_mfma_f32_16x16x32_bf16 v[78:81], v[148:151], v[178:181], v[78:81]
	v_mfma_f32_16x16x32_bf16 v[106:109], v[140:143], v[186:189], v[106:109]
	v_mfma_f32_16x16x32_bf16 v[74:77], v[148:151], v[186:189], v[74:77]
	v_mfma_f32_16x16x32_bf16 v[102:105], v[140:143], v[210:213], v[102:105]
	v_mfma_f32_16x16x32_bf16 v[70:73], v[148:151], v[210:213], v[70:73]
	v_mfma_f32_16x16x32_bf16 v[98:101], v[140:143], v[218:221], v[98:101]
	v_mfma_f32_16x16x32_bf16 v[66:69], v[148:151], v[218:221], v[66:69]
	v_mfma_f32_16x16x32_bf16 v[46:49], v[152:155], v[168:171], v[46:49]
	v_mfma_f32_16x16x32_bf16 v[14:17], v[160:163], v[168:171], v[14:17]
	v_mfma_f32_16x16x32_bf16 v[42:45], v[152:155], v[182:185], v[42:45]
	v_mfma_f32_16x16x32_bf16 v[10:13], v[160:163], v[182:185], v[10:13]
	v_mfma_f32_16x16x32_bf16 v[34:37], v[152:155], v[190:193], v[34:37]
	v_mfma_f32_16x16x32_bf16 v[6:9], v[160:163], v[190:193], v[6:9]
	v_mfma_f32_16x16x32_bf16 v[26:29], v[152:155], v[214:217], v[26:29]
	v_mfma_f32_16x16x32_bf16 v[2:5], v[160:163], v[214:217], v[2:5]
	v_mfma_f32_16x16x32_bf16 v[46:49], v[156:159], v[178:181], v[46:49]
	v_mfma_f32_16x16x32_bf16 v[14:17], v[164:167], v[178:181], v[14:17]
	v_mfma_f32_16x16x32_bf16 v[42:45], v[156:159], v[186:189], v[42:45]
	v_mfma_f32_16x16x32_bf16 v[10:13], v[164:167], v[186:189], v[10:13]
	v_mfma_f32_16x16x32_bf16 v[34:37], v[156:159], v[210:213], v[34:37]
	v_mfma_f32_16x16x32_bf16 v[6:9], v[164:167], v[210:213], v[6:9]
	v_mfma_f32_16x16x32_bf16 v[26:29], v[156:159], v[218:221], v[26:29]
	v_mfma_f32_16x16x32_bf16 v[2:5], v[164:167], v[218:221], v[2:5]
	s_barrier
	s_add_i32 s91, 0, 0x18000
	s_add_i32 s94, 0, 0x1c000
	v_add_u32_e32 v148, s91, v175
	v_add_u32_e32 v164, s94, v175
	ds_read_b128 v[136:139], v148
	ds_read_b128 v[140:143], v148 offset:1024
	ds_read_b128 v[144:147], v148 offset:2048
	ds_read_b128 v[148:151], v148 offset:3072
	ds_read_b128 v[152:155], v164
	ds_read_b128 v[156:159], v164 offset:1024
	ds_read_b128 v[160:163], v164 offset:2048
	ds_read_b128 v[164:167], v164 offset:3072
	v_lshl_add_u64 v[172:173], s[92:93], 0, v[0:1]
	s_mov_b32 m0, s56
	s_nop 0
	global_load_lds_dwordx4 v[172:173], off
	v_lshl_add_u64 v[172:173], s[92:93], 0, v[130:131]
	s_mov_b32 m0, s58
	s_nop 0
	global_load_lds_dwordx4 v[172:173], off
	s_add_u32 s92, s92, 0x4000
	s_addc_u32 s93, s93, 0
	s_mov_b32 m0, s63
	v_lshl_add_u64 v[172:173], s[92:93], 0, v[0:1]
	ds_read_b128 v[168:171], v177 offset:32768
	ds_read_b128 v[178:181], v177 offset:33792
	ds_read_b128 v[182:185], v177 offset:34816
	ds_read_b128 v[186:189], v177 offset:35840
	ds_read_b128 v[190:193], v177 offset:36864
	ds_read_b128 v[210:213], v177 offset:37888
	ds_read_b128 v[214:217], v177 offset:38912
	ds_read_b128 v[218:221], v177 offset:39936
	global_load_lds_dwordx4 v[172:173], off
	v_lshl_add_u64 v[172:173], s[92:93], 0, v[130:131]
	s_mov_b32 m0, s64
	s_nop 0
	global_load_lds_dwordx4 v[172:173], off
	s_waitcnt vmcnt(8)
	s_waitcnt lgkmcnt(0)
	s_barrier
; #define PG8_STAGE(bufoff, gbase, voff) do { _Pragma("unroll") for (int _i = 0; _i < 2; ++_i) \
;         __builtin_amdgcn_global_load_lds((const unsigned*)((const char*)(gbase) + (voff)[_i]), (LAS unsigned*)(lds + (bufoff) + ldsw + _i * 8192), 16, 0, 0); } while (0)
; #define PG8_LDA(dst, b, h) do { _Pragma("unroll") for (int m = 0; m < 4; ++m) _Pragma("unroll") for (int k = 0; k < 2; ++k) dst[m][k] = *(const LAS bf16x8*)(lds + PG8_SA(b, h) + aoff + m * 2048 + k * 1024); } while (0)
; #define PG8_MMA(ai, bj, At, Bt) do { __builtin_amdgcn_s_setprio(1); _Pragma("unroll") for (int m = 0; m < 4; ++m) _Pragma("unroll") for (int n = 0; n < 2; ++n) _Pragma("unroll") for (int k = 0; k < 2; ++k) \
;         acc[ai][bj][m][n] = __builtin_amdgcn_mfma_f32_16x16x32_bf16(Bt[n][k], At[m][k], acc[ai][bj][m][n], 0, 0, 0); __builtin_amdgcn_s_setprio(0); } while (0)
; #define PG8_WAIT_V(n) asm volatile("s_waitcnt vmcnt(" #n ")" ::: "memory")
; #define PG8_WAIT_L(n) asm volatile("s_waitcnt lgkmcnt(" #n ")" ::: "memory")
; #define PG8_BAR __builtin_amdgcn_s_barrier()
; #define PG8_SCHED __builtin_amdgcn_sched_barrier(0)
; template <class Epi, bool ALIGN_EPI>
; __device__ __forceinline__ void gemm_phase(LAS unsigned char* lds, const int tid, const Gemm g, const StaticOrder& S, const Epi& E) {
;     ...
;             PG8_WAIT_V(8); PG8_WAIT_L(0); PG8_BAR; PG8_MMA(0, 0, At, B0); PG8_MMA(0, 1, At, B1); PG8_BAR; PG8_SCHED;
;             PG8_LDA(At, 1, 1); PG8_STAGE(PG8_SB(1, 0), b3, voffB); PG8_STAGE(PG8_SB(1, 1), b3 + hstepB, voffB); PG8_STAGE(PG8_SA(1, 0), a3, voffA);
;             PG8_WAIT_V(8); PG8_WAIT_L(0); PG8_BAR; PG8_MMA(1, 0, At, B0); PG8_MMA(1, 1, At, B1); PG8_BAR; PG8_SCHED;
;         }
	v_mfma_f32_16x16x32_bf16 v[126:129], v[136:139], v[168:171], v[126:129]
	v_mfma_f32_16x16x32_bf16 v[94:97], v[144:147], v[168:171], v[94:97]
	v_mfma_f32_16x16x32_bf16 v[122:125], v[136:139], v[182:185], v[122:125]
	v_mfma_f32_16x16x32_bf16 v[90:93], v[144:147], v[182:185], v[90:93]
	v_mfma_f32_16x16x32_bf16 v[118:121], v[136:139], v[190:193], v[118:121]
	v_mfma_f32_16x16x32_bf16 v[86:89], v[144:147], v[190:193], v[86:89]
	v_mfma_f32_16x16x32_bf16 v[114:117], v[136:139], v[214:217], v[114:117]
	v_mfma_f32_16x16x32_bf16 v[82:85], v[144:147], v[214:217], v[82:85]
	v_mfma_f32_16x16x32_bf16 v[126:129], v[140:143], v[178:181], v[126:129]
	v_mfma_f32_16x16x32_bf16 v[94:97], v[148:151], v[178:181], v[94:97]
	v_mfma_f32_16x16x32_bf16 v[122:125], v[140:143], v[186:189], v[122:125]
	v_mfma_f32_16x16x32_bf16 v[90:93], v[148:151], v[186:189], v[90:93]
	v_mfma_f32_16x16x32_bf16 v[118:121], v[140:143], v[210:213], v[118:121]
	v_mfma_f32_16x16x32_bf16 v[86:89], v[148:151], v[210:213], v[86:89]
	v_mfma_f32_16x16x32_bf16 v[114:117], v[140:143], v[218:221], v[114:117]
	v_mfma_f32_16x16x32_bf16 v[82:85], v[148:151], v[218:221], v[82:85]
	v_mfma_f32_16x16x32_bf16 v[62:65], v[152:155], v[168:171], v[62:65]
	v_mfma_f32_16x16x32_bf16 v[38:41], v[160:163], v[168:171], v[38:41]
	v_mfma_f32_16x16x32_bf16 v[58:61], v[152:155], v[182:185], v[58:61]
	v_mfma_f32_16x16x32_bf16 v[30:33], v[160:163], v[182:185], v[30:33]
	v_mfma_f32_16x16x32_bf16 v[54:57], v[152:155], v[190:193], v[54:57]
	v_mfma_f32_16x16x32_bf16 v[22:25], v[160:163], v[190:193], v[22:25]
	v_mfma_f32_16x16x32_bf16 v[50:53], v[152:155], v[214:217], v[50:53]
	v_mfma_f32_16x16x32_bf16 v[18:21], v[160:163], v[214:217], v[18:21]
	v_mfma_f32_16x16x32_bf16 v[62:65], v[156:159], v[178:181], v[62:65]
	v_mfma_f32_16x16x32_bf16 v[38:41], v[164:167], v[178:181], v[38:41]
	v_mfma_f32_16x16x32_bf16 v[58:61], v[156:159], v[186:189], v[58:61]
	v_mfma_f32_16x16x32_bf16 v[30:33], v[164:167], v[186:189], v[30:33]
	v_mfma_f32_16x16x32_bf16 v[54:57], v[156:159], v[210:213], v[54:57]
	v_mfma_f32_16x16x32_bf16 v[22:25], v[164:167], v[210:213], v[22:25]
	v_mfma_f32_16x16x32_bf16 v[50:53], v[156:159], v[218:221], v[50:53]
	v_mfma_f32_16x16x32_bf16 v[18:21], v[164:167], v[218:221], v[18:21]
	s_barrier
	s_add_u32 s92, s54, 0x40000
	s_addc_u32 s93, s55, 0
	s_add_i32 s91, s91, s29
	v_lshl_add_u64 v[172:173], s[92:93], 0, v[0:1]
	s_mov_b32 m0, s91
	ds_read_b128 v[168:171], v177 offset:49152
	ds_read_b128 v[178:181], v177 offset:50176
	ds_read_b128 v[182:185], v177 offset:51200
	ds_read_b128 v[186:189], v177 offset:52224
	ds_read_b128 v[190:193], v177 offset:53248
	ds_read_b128 v[210:213], v177 offset:54272
	ds_read_b128 v[214:217], v177 offset:55296
	ds_read_b128 v[218:221], v177 offset:56320
	global_load_lds_dwordx4 v[172:173], off
	s_add_i32 m0, s91, 0x2000
	s_add_u32 s54, s54, 0x44000
	v_lshl_add_u64 v[172:173], s[92:93], 0, v[130:131]
	s_addc_u32 s55, s55, 0
	s_add_i32 s91, s94, s29
	global_load_lds_dwordx4 v[172:173], off
	v_lshl_add_u64 v[172:173], s[54:55], 0, v[0:1]
	s_mov_b32 m0, s91
	s_nop 0
	global_load_lds_dwordx4 v[172:173], off
	v_lshl_add_u64 v[172:173], s[54:55], 0, v[130:131]
	s_add_i32 m0, s91, 0x2000
	s_nop 0
	global_load_lds_dwordx4 v[172:173], off
	s_waitcnt vmcnt(4)
	s_waitcnt lgkmcnt(0)
	s_barrier
	v_mfma_f32_16x16x32_bf16 v[110:113], v[136:139], v[168:171], v[110:113]
	v_mfma_f32_16x16x32_bf16 v[78:81], v[144:147], v[168:171], v[78:81]
	v_mfma_f32_16x16x32_bf16 v[106:109], v[136:139], v[182:185], v[106:109]
	v_mfma_f32_16x16x32_bf16 v[74:77], v[144:147], v[182:185], v[74:77]
	v_mfma_f32_16x16x32_bf16 v[102:105], v[136:139], v[190:193], v[102:105]
	v_mfma_f32_16x16x32_bf16 v[70:73], v[144:147], v[190:193], v[70:73]
	v_mfma_f32_16x16x32_bf16 v[98:101], v[136:139], v[214:217], v[98:101]
	v_mfma_f32_16x16x32_bf16 v[66:69], v[144:147], v[214:217], v[66:69]
	v_mfma_f32_16x16x32_bf16 v[110:113], v[140:143], v[178:181], v[110:113]
	v_mfma_f32_16x16x32_bf16 v[78:81], v[148:151], v[178:181], v[78:81]
	v_mfma_f32_16x16x32_bf16 v[106:109], v[140:143], v[186:189], v[106:109]
	v_mfma_f32_16x16x32_bf16 v[74:77], v[148:151], v[186:189], v[74:77]
	v_mfma_f32_16x16x32_bf16 v[102:105], v[140:143], v[210:213], v[102:105]
	v_mfma_f32_16x16x32_bf16 v[70:73], v[148:151], v[210:213], v[70:73]
	v_mfma_f32_16x16x32_bf16 v[98:101], v[140:143], v[218:221], v[98:101]
	v_mfma_f32_16x16x32_bf16 v[66:69], v[148:151], v[218:221], v[66:69]
	v_mfma_f32_16x16x32_bf16 v[46:49], v[152:155], v[168:171], v[46:49]
	v_mfma_f32_16x16x32_bf16 v[14:17], v[160:163], v[168:171], v[14:17]
	v_mfma_f32_16x16x32_bf16 v[42:45], v[152:155], v[182:185], v[42:45]
	v_mfma_f32_16x16x32_bf16 v[10:13], v[160:163], v[182:185], v[10:13]
	v_mfma_f32_16x16x32_bf16 v[34:37], v[152:155], v[190:193], v[34:37]
	v_mfma_f32_16x16x32_bf16 v[6:9], v[160:163], v[190:193], v[6:9]
	v_mfma_f32_16x16x32_bf16 v[26:29], v[152:155], v[214:217], v[26:29]
	v_mfma_f32_16x16x32_bf16 v[2:5], v[160:163], v[214:217], v[2:5]
	v_mfma_f32_16x16x32_bf16 v[46:49], v[156:159], v[178:181], v[46:49]
	v_mfma_f32_16x16x32_bf16 v[14:17], v[164:167], v[178:181], v[14:17]
	v_mfma_f32_16x16x32_bf16 v[42:45], v[156:159], v[186:189], v[42:45]
	v_mfma_f32_16x16x32_bf16 v[10:13], v[164:167], v[186:189], v[10:13]
	v_mfma_f32_16x16x32_bf16 v[34:37], v[156:159], v[210:213], v[34:37]
	v_mfma_f32_16x16x32_bf16 v[6:9], v[164:167], v[210:213], v[6:9]
	v_mfma_f32_16x16x32_bf16 v[26:29], v[156:159], v[218:221], v[26:29]
	v_mfma_f32_16x16x32_bf16 v[2:5], v[164:167], v[218:221], v[2:5]
	s_barrier
	s_add_u32 s25, s25, 0x80000
	s_addc_u32 s27, s27, 0
	s_add_u32 s30, s30, 0x240000
	s_addc_u32 s31, s31, 0
	s_cmp_ge_u32 s90, s17
	s_cbranch_scc1 .LBB0_116

; #define PG8_BAR __builtin_amdgcn_s_barrier()
; template <class Epi, bool ALIGN_EPI>
; __device__ __forceinline__ void gemm_phase(LAS unsigned char* lds, const int tid, const Gemm g, const StaticOrder& S, const Epi& E) {
;     ...
;         if constexpr (ALIGN_EPI) { if (wr == 0) PG8_BAR; }
;         E(acc, cur, wr, wc, fr, fq);
.LBB0_116:
	s_and_b64 vcc, exec, s[14:15]
	s_cbranch_vccz .LBB0_118
	s_barrier
	s_setprio 1

; #define PG8_STAGE(bufoff, gbase, voff) do { _Pragma("unroll") for (int _i = 0; _i < 2; ++_i) \
;         __builtin_amdgcn_global_load_lds((const unsigned*)((const char*)(gbase) + (voff)[_i]), (LAS unsigned*)(lds + (bufoff) + ldsw + _i * 8192), 16, 0, 0); } while (0)
; #define PG8_LDA(dst, b, h) do { _Pragma("unroll") for (int m = 0; m < 4; ++m) _Pragma("unroll") for (int k = 0; k < 2; ++k) dst[m][k] = *(const LAS bf16x8*)(lds + PG8_SA(b, h) + aoff + m * 2048 + k * 1024); } while (0)
; #define PG8_LDB(dst, b, h) do { _Pragma("unroll") for (int n = 0; n < 2; ++n) _Pragma("unroll") for (int k = 0; k < 2; ++k) dst[n][k] = *(const LAS bf16x8*)(lds + PG8_SB(b, h) + boff + n * 2048 + k * 1024); } while (0)
; #define PG8_WAIT_V(n) asm volatile("s_waitcnt vmcnt(" #n ")" ::: "memory")
; #define PG8_WAIT_L(n) asm volatile("s_waitcnt lgkmcnt(" #n ")" ::: "memory")
; #define PG8_BAR __builtin_amdgcn_s_barrier()
; template <class Epi, bool ALIGN_EPI>
; __device__ __forceinline__ void gemm_phase(LAS unsigned char* lds, const int tid, const Gemm g, const StaticOrder& S, const Epi& E) {
;     ...
;         const bool has_next = S.next(ui + 1, nxt);
;         const char* nA = has_next ? (const char*)g.A + (size_t)nxt.pm * tstepA + PG8_KOFFA(nxt) : cA; const char* nB = has_next ? (const char*)g.Bt + (size_t)nxt.pn * tstepB + PG8_KOFFB(nxt) : cB;
;         const int nt = cur.ks >= 0 ? nt_split : nt_full;
;         for (int t = 0; t < nt; t += 2) {
;             if constexpr (Epi::HOOK) { if (t != 0 && (t & 7) == 0) E.hook(acc, cur, (t >> 3) - 1, wr, wc, fr, fq); }
;             const bool last = (t == nt - 2);
;             const char* a1 = cA + (size_t)(t + 1) * kstepA;
;             const char* a2 = last ? nA : cA + (size_t)(t + 2) * kstepA; const char* b2 = last ? nB : cB + (size_t)(t + 2) * kstepB;
;             const char* a3 = a2 + kstepA; const char* b3 = b2 + kstepB;
;             PG8_LDB(B0, 0, 0); PG8_LDB(B1, 0, 1); PG8_SCHED; PG8_LDA(At, 0, 0); PG8_STAGE(PG8_SA(1, 1), a1 + hstepA, voffA);
;             PG8_WAIT_V(8); PG8_WAIT_L(0); PG8_BAR; PG8_MMA(0, 0, At, B0); PG8_MMA(0, 1, At, B1); PG8_BAR; PG8_SCHED;
;             PG8_LDA(At, 0, 1); PG8_STAGE(PG8_SB(0, 0), b2, voffB); PG8_STAGE(PG8_SB(0, 1), b2 + hstepB, voffB); PG8_STAGE(PG8_SA(0, 0), a2, voffA);
;             PG8_WAIT_V(8); PG8_WAIT_L(0); PG8_BAR; PG8_MMA(1, 0, At, B0); PG8_MMA(1, 1, At, B1); PG8_BAR; PG8_SCHED;
.LBB0_143:
	s_setprio 0
	s_add_u32 s26, s24, 0xfff80080
	s_addc_u32 s27, s25, -1
	s_add_i32 s68, 0, 0x10000
	s_cmp_eq_u32 s67, 28
	s_cselect_b32 s29, s19, s27
	s_cselect_b32 s28, s18, s26
	v_add_u32_e32 v142, s68, v145
	s_cselect_b32 s27, s21, s17
	s_cselect_b32 s26, s20, s15
	s_add_i32 s70, 0, 0x14000
	ds_read_b128 v[148:151], v142
	ds_read_b128 v[152:155], v142 offset:1024
	ds_read_b128 v[156:159], v142 offset:2048
	ds_read_b128 v[160:163], v142 offset:3072
	v_add_u32_e32 v142, s70, v145
	ds_read_b128 v[164:167], v142
	ds_read_b128 v[168:171], v142 offset:1024
	ds_read_b128 v[172:175], v142 offset:2048
	ds_read_b128 v[176:179], v142 offset:3072
	v_lshl_add_u64 v[142:143], s[24:25], 0, v[140:141]
	s_add_i32 m0, s23, 0xc000
	ds_read_b128 v[180:183], v146
	ds_read_b128 v[184:187], v146 offset:1024
	ds_read_b128 v[188:191], v146 offset:2048
	ds_read_b128 v[192:195], v146 offset:3072
	ds_read_b128 v[210:213], v146 offset:4096
	ds_read_b128 v[214:217], v146 offset:5120
	ds_read_b128 v[218:221], v146 offset:6144
	ds_read_b128 v[222:225], v146 offset:7168
	global_load_lds_dwordx4 v[142:143], off
	v_lshl_add_u64 v[142:143], s[24:25], 0, v[138:139]
	s_add_i32 m0, s23, 0xe000
	s_nop 0
	global_load_lds_dwordx4 v[142:143], off
	s_sub_u32 s98, s24, 0x80000
	s_subb_u32 s99, s25, 0
	v_lshl_add_u64 v[142:143], s[98:99], 0, v[140:141]
	s_mov_b32 m0, s56
	s_nop 0
	global_load_lds_dwordx4 v[142:143], off
	v_lshl_add_u64 v[142:143], s[98:99], 0, v[138:139]
	s_mov_b32 m0, s58
	s_nop 0
	global_load_lds_dwordx4 v[142:143], off
	s_waitcnt vmcnt(8)
	s_waitcnt lgkmcnt(0)
	s_barrier
	v_mfma_f32_16x16x32_bf16 v[126:129], v[148:151], v[180:183], v[126:129]
	v_mfma_f32_16x16x32_bf16 v[122:125], v[156:159], v[180:183], v[122:125]
	v_mfma_f32_16x16x32_bf16 v[110:113], v[148:151], v[188:191], v[110:113]
	v_mfma_f32_16x16x32_bf16 v[106:109], v[156:159], v[188:191], v[106:109]
	v_mfma_f32_16x16x32_bf16 v[94:97], v[148:151], v[210:213], v[94:97]
	v_mfma_f32_16x16x32_bf16 v[90:93], v[156:159], v[210:213], v[90:93]
	v_mfma_f32_16x16x32_bf16 v[78:81], v[148:151], v[218:221], v[78:81]
	v_mfma_f32_16x16x32_bf16 v[74:77], v[156:159], v[218:221], v[74:77]
	v_mfma_f32_16x16x32_bf16 v[126:129], v[152:155], v[184:187], v[126:129]
	v_mfma_f32_16x16x32_bf16 v[122:125], v[160:163], v[184:187], v[122:125]
	v_mfma_f32_16x16x32_bf16 v[110:113], v[152:155], v[192:195], v[110:113]
	v_mfma_f32_16x16x32_bf16 v[106:109], v[160:163], v[192:195], v[106:109]
	v_mfma_f32_16x16x32_bf16 v[94:97], v[152:155], v[214:217], v[94:97]
	v_mfma_f32_16x16x32_bf16 v[90:93], v[160:163], v[214:217], v[90:93]
	v_mfma_f32_16x16x32_bf16 v[78:81], v[152:155], v[222:225], v[78:81]
	v_mfma_f32_16x16x32_bf16 v[74:77], v[160:163], v[222:225], v[74:77]
	v_mfma_f32_16x16x32_bf16 v[118:121], v[164:167], v[180:183], v[118:121]
	v_mfma_f32_16x16x32_bf16 v[114:117], v[172:175], v[180:183], v[114:117]
	v_mfma_f32_16x16x32_bf16 v[102:105], v[164:167], v[188:191], v[102:105]
	v_mfma_f32_16x16x32_bf16 v[98:101], v[172:175], v[188:191], v[98:101]
	v_mfma_f32_16x16x32_bf16 v[86:89], v[164:167], v[210:213], v[86:89]
	v_mfma_f32_16x16x32_bf16 v[82:85], v[172:175], v[210:213], v[82:85]
	v_mfma_f32_16x16x32_bf16 v[70:73], v[164:167], v[218:221], v[70:73]
	v_mfma_f32_16x16x32_bf16 v[66:69], v[172:175], v[218:221], v[66:69]
	v_mfma_f32_16x16x32_bf16 v[118:121], v[168:171], v[184:187], v[118:121]
	v_mfma_f32_16x16x32_bf16 v[114:117], v[176:179], v[184:187], v[114:117]
	v_mfma_f32_16x16x32_bf16 v[102:105], v[168:171], v[192:195], v[102:105]
	v_mfma_f32_16x16x32_bf16 v[98:101], v[176:179], v[192:195], v[98:101]
	v_mfma_f32_16x16x32_bf16 v[86:89], v[168:171], v[214:217], v[86:89]
	v_mfma_f32_16x16x32_bf16 v[82:85], v[176:179], v[214:217], v[82:85]
	v_mfma_f32_16x16x32_bf16 v[70:73], v[168:171], v[222:225], v[70:73]
	v_mfma_f32_16x16x32_bf16 v[66:69], v[176:179], v[222:225], v[66:69]
	s_barrier
	s_add_i32 s68, s68, s30
	v_lshl_add_u64 v[142:143], s[26:27], 0, v[0:1]
	s_mov_b32 m0, s68
	ds_read_b128 v[180:183], v146 offset:16384
	ds_read_b128 v[184:187], v146 offset:17408
	ds_read_b128 v[188:191], v146 offset:18432
	ds_read_b128 v[192:195], v146 offset:19456
	ds_read_b128 v[210:213], v146 offset:20480
	ds_read_b128 v[214:217], v146 offset:21504
	ds_read_b128 v[218:221], v146 offset:22528
	ds_read_b128 v[222:225], v146 offset:23552
	global_load_lds_dwordx4 v[142:143], off
	s_add_i32 m0, s68, 0x2000
	s_add_u32 s68, s26, 0x80000
	v_lshl_add_u64 v[240:241], s[26:27], 0, v[130:131]
	s_addc_u32 s69, s27, 0
	s_add_i32 s70, s70, s30
	global_load_lds_dwordx4 v[240:241], off
	v_lshl_add_u64 v[242:243], s[68:69], 0, v[0:1]
	s_mov_b32 m0, s70
	v_lshl_add_u64 v[244:245], s[28:29], 0, v[132:133]
	global_load_lds_dwordx4 v[242:243], off
	v_lshl_add_u64 v[242:243], s[68:69], 0, v[130:131]
	s_add_i32 m0, s70, 0x2000
	s_nop 0
	global_load_lds_dwordx4 v[242:243], off
	v_lshl_add_u64 v[242:243], s[28:29], 0, v[134:135]
	s_waitcnt vmcnt(4)
	s_waitcnt lgkmcnt(0)
	s_barrier
; #define PG8_STAGE(bufoff, gbase, voff) do { _Pragma("unroll") for (int _i = 0; _i < 2; ++_i) \
;         __builtin_amdgcn_global_load_lds((const unsigned*)((const char*)(gbase) + (voff)[_i]), (LAS unsigned*)(lds + (bufoff) + ldsw + _i * 8192), 16, 0, 0); } while (0)
; #define PG8_LDA(dst, b, h) do { _Pragma("unroll") for (int m = 0; m < 4; ++m) _Pragma("unroll") for (int k = 0; k < 2; ++k) dst[m][k] = *(const LAS bf16x8*)(lds + PG8_SA(b, h) + aoff + m * 2048 + k * 1024); } while (0)
; #define PG8_LDB(dst, b, h) do { _Pragma("unroll") for (int n = 0; n < 2; ++n) _Pragma("unroll") for (int k = 0; k < 2; ++k) dst[n][k] = *(const LAS bf16x8*)(lds + PG8_SB(b, h) + boff + n * 2048 + k * 1024); } while (0)
; #define PG8_MMA(ai, bj, At, Bt) do { __builtin_amdgcn_s_setprio(1); _Pragma("unroll") for (int m = 0; m < 4; ++m) _Pragma("unroll") for (int n = 0; n < 2; ++n) _Pragma("unroll") for (int k = 0; k < 2; ++k) \
;         acc[ai][bj][m][n] = __builtin_amdgcn_mfma_f32_16x16x32_bf16(Bt[n][k], At[m][k], acc[ai][bj][m][n], 0, 0, 0); __builtin_amdgcn_s_setprio(0); } while (0)
; #define PG8_WAIT_V(n) asm volatile("s_waitcnt vmcnt(" #n ")" ::: "memory")
; #define PG8_WAIT_L(n) asm volatile("s_waitcnt lgkmcnt(" #n ")" ::: "memory")
; #define PG8_BAR __builtin_amdgcn_s_barrier()
; #define PG8_SCHED __builtin_amdgcn_sched_barrier(0)
; template <class Epi, bool ALIGN_EPI>
; __device__ __forceinline__ void gemm_phase(LAS unsigned char* lds, const int tid, const Gemm g, const StaticOrder& S, const Epi& E) {
;     ...
;             PG8_WAIT_V(8); PG8_WAIT_L(0); PG8_BAR; PG8_MMA(1, 0, At, B0); PG8_MMA(1, 1, At, B1); PG8_BAR; PG8_SCHED;
;             PG8_LDB(B0, 1, 0); PG8_LDB(B1, 1, 1); PG8_SCHED; PG8_LDA(At, 1, 0); PG8_STAGE(PG8_SA(0, 1), a2 + hstepA, voffA);
;             PG8_WAIT_V(8); PG8_WAIT_L(0); PG8_BAR; PG8_MMA(0, 0, At, B0); PG8_MMA(0, 1, At, B1); PG8_BAR; PG8_SCHED;
	v_mfma_f32_16x16x32_bf16 v[62:65], v[148:151], v[180:183], v[62:65]
	v_mfma_f32_16x16x32_bf16 v[58:61], v[156:159], v[180:183], v[58:61]
	v_mfma_f32_16x16x32_bf16 v[46:49], v[148:151], v[188:191], v[46:49]
	v_mfma_f32_16x16x32_bf16 v[42:45], v[156:159], v[188:191], v[42:45]
	v_mfma_f32_16x16x32_bf16 v[30:33], v[148:151], v[210:213], v[30:33]
	v_mfma_f32_16x16x32_bf16 v[26:29], v[156:159], v[210:213], v[26:29]
	v_mfma_f32_16x16x32_bf16 v[14:17], v[148:151], v[218:221], v[14:17]
	v_mfma_f32_16x16x32_bf16 v[10:13], v[156:159], v[218:221], v[10:13]
	v_mfma_f32_16x16x32_bf16 v[62:65], v[152:155], v[184:187], v[62:65]
	v_mfma_f32_16x16x32_bf16 v[58:61], v[160:163], v[184:187], v[58:61]
	v_mfma_f32_16x16x32_bf16 v[46:49], v[152:155], v[192:195], v[46:49]
	v_mfma_f32_16x16x32_bf16 v[42:45], v[160:163], v[192:195], v[42:45]
	v_mfma_f32_16x16x32_bf16 v[30:33], v[152:155], v[214:217], v[30:33]
	v_mfma_f32_16x16x32_bf16 v[26:29], v[160:163], v[214:217], v[26:29]
	v_mfma_f32_16x16x32_bf16 v[14:17], v[152:155], v[222:225], v[14:17]
	v_mfma_f32_16x16x32_bf16 v[10:13], v[160:163], v[222:225], v[10:13]
	v_mfma_f32_16x16x32_bf16 v[54:57], v[164:167], v[180:183], v[54:57]
	v_mfma_f32_16x16x32_bf16 v[50:53], v[172:175], v[180:183], v[50:53]
	v_mfma_f32_16x16x32_bf16 v[38:41], v[164:167], v[188:191], v[38:41]
	v_mfma_f32_16x16x32_bf16 v[34:37], v[172:175], v[188:191], v[34:37]
	v_mfma_f32_16x16x32_bf16 v[22:25], v[164:167], v[210:213], v[22:25]
	v_mfma_f32_16x16x32_bf16 v[18:21], v[172:175], v[210:213], v[18:21]
	v_mfma_f32_16x16x32_bf16 v[6:9], v[164:167], v[218:221], v[6:9]
	v_mfma_f32_16x16x32_bf16 v[2:5], v[172:175], v[218:221], v[2:5]
	v_mfma_f32_16x16x32_bf16 v[54:57], v[168:171], v[184:187], v[54:57]
	v_mfma_f32_16x16x32_bf16 v[50:53], v[176:179], v[184:187], v[50:53]
	v_mfma_f32_16x16x32_bf16 v[38:41], v[168:171], v[192:195], v[38:41]
	v_mfma_f32_16x16x32_bf16 v[34:37], v[176:179], v[192:195], v[34:37]
	v_mfma_f32_16x16x32_bf16 v[22:25], v[168:171], v[214:217], v[22:25]
	v_mfma_f32_16x16x32_bf16 v[18:21], v[176:179], v[214:217], v[18:21]
	v_mfma_f32_16x16x32_bf16 v[6:9], v[168:171], v[222:225], v[6:9]
	v_mfma_f32_16x16x32_bf16 v[2:5], v[176:179], v[222:225], v[2:5]
	s_barrier
	s_add_i32 s68, 0, 0x18000
	v_add_u32_e32 v147, s68, v145
	s_add_i32 s69, 0, 0x1c000
	ds_read_b128 v[148:151], v147
	ds_read_b128 v[152:155], v147 offset:1024
	ds_read_b128 v[156:159], v147 offset:2048
	ds_read_b128 v[160:163], v147 offset:3072
	v_add_u32_e32 v147, s69, v145
	ds_read_b128 v[164:167], v147
	ds_read_b128 v[168:171], v147 offset:1024
	ds_read_b128 v[172:175], v147 offset:2048
	ds_read_b128 v[176:179], v147 offset:3072
	s_mov_b32 m0, s23
	s_nop 0
	global_load_lds_dwordx4 v[242:243], off
	s_mov_b32 m0, s52
	s_nop 0
	global_load_lds_dwordx4 v[244:245], off
	s_add_u32 s28, s28, 0x80000
	s_addc_u32 s29, s29, 0
	s_mov_b32 m0, s54
	v_lshl_add_u64 v[246:247], s[28:29], 0, v[134:135]
	ds_read_b128 v[180:183], v146 offset:32768
	ds_read_b128 v[184:187], v146 offset:33792
	ds_read_b128 v[188:191], v146 offset:34816
	ds_read_b128 v[192:195], v146 offset:35840
	ds_read_b128 v[210:213], v146 offset:36864
	ds_read_b128 v[214:217], v146 offset:37888
	ds_read_b128 v[218:221], v146 offset:38912
	ds_read_b128 v[222:225], v146 offset:39936
	global_load_lds_dwordx4 v[246:247], off
	v_lshl_add_u64 v[246:247], s[28:29], 0, v[132:133]
	s_mov_b32 m0, s55
	s_nop 0
	global_load_lds_dwordx4 v[246:247], off
	s_waitcnt vmcnt(8)
	s_waitcnt lgkmcnt(0)
	s_barrier
; #define PG8_STAGE(bufoff, gbase, voff) do { _Pragma("unroll") for (int _i = 0; _i < 2; ++_i) \
;         __builtin_amdgcn_global_load_lds((const unsigned*)((const char*)(gbase) + (voff)[_i]), (LAS unsigned*)(lds + (bufoff) + ldsw + _i * 8192), 16, 0, 0); } while (0)
; #define PG8_LDA(dst, b, h) do { _Pragma("unroll") for (int m = 0; m < 4; ++m) _Pragma("unroll") for (int k = 0; k < 2; ++k) dst[m][k] = *(const LAS bf16x8*)(lds + PG8_SA(b, h) + aoff + m * 2048 + k * 1024); } while (0)
; #define PG8_MMA(ai, bj, At, Bt) do { __builtin_amdgcn_s_setprio(1); _Pragma("unroll") for (int m = 0; m < 4; ++m) _Pragma("unroll") for (int n = 0; n < 2; ++n) _Pragma("unroll") for (int k = 0; k < 2; ++k) \
;         acc[ai][bj][m][n] = __builtin_amdgcn_mfma_f32_16x16x32_bf16(Bt[n][k], At[m][k], acc[ai][bj][m][n], 0, 0, 0); __builtin_amdgcn_s_setprio(0); } while (0)
; #define PG8_WAIT_V(n) asm volatile("s_waitcnt vmcnt(" #n ")" ::: "memory")
; #define PG8_WAIT_L(n) asm volatile("s_waitcnt lgkmcnt(" #n ")" ::: "memory")
; #define PG8_BAR __builtin_amdgcn_s_barrier()
; #define PG8_SCHED __builtin_amdgcn_sched_barrier(0)
; template <class Epi, bool ALIGN_EPI>
; __device__ __forceinline__ void gemm_phase(LAS unsigned char* lds, const int tid, const Gemm g, const StaticOrder& S, const Epi& E) {
;     ...
;             PG8_WAIT_V(8); PG8_WAIT_L(0); PG8_BAR; PG8_MMA(0, 0, At, B0); PG8_MMA(0, 1, At, B1); PG8_BAR; PG8_SCHED;
;             PG8_LDA(At, 1, 1); PG8_STAGE(PG8_SB(1, 0), b3, voffB); PG8_STAGE(PG8_SB(1, 1), b3 + hstepB, voffB); PG8_STAGE(PG8_SA(1, 0), a3, voffA);
;             PG8_WAIT_V(8); PG8_WAIT_L(0); PG8_BAR; PG8_MMA(1, 0, At, B0); PG8_MMA(1, 1, At, B1); PG8_BAR; PG8_SCHED;
;         }
;         if constexpr (ALIGN_EPI) { if (wr == 0) PG8_BAR; }
;         E(acc, cur, wr, wc, fr, fq);
	v_mfma_f32_16x16x32_bf16 v[126:129], v[148:151], v[180:183], v[126:129]
	v_mfma_f32_16x16x32_bf16 v[122:125], v[156:159], v[180:183], v[122:125]
	v_mfma_f32_16x16x32_bf16 v[110:113], v[148:151], v[188:191], v[110:113]
	v_mfma_f32_16x16x32_bf16 v[106:109], v[156:159], v[188:191], v[106:109]
	v_mfma_f32_16x16x32_bf16 v[94:97], v[148:151], v[210:213], v[94:97]
	v_mfma_f32_16x16x32_bf16 v[90:93], v[156:159], v[210:213], v[90:93]
	v_mfma_f32_16x16x32_bf16 v[78:81], v[148:151], v[218:221], v[78:81]
	v_mfma_f32_16x16x32_bf16 v[74:77], v[156:159], v[218:221], v[74:77]
	v_mfma_f32_16x16x32_bf16 v[126:129], v[152:155], v[184:187], v[126:129]
	v_mfma_f32_16x16x32_bf16 v[122:125], v[160:163], v[184:187], v[122:125]
	v_mfma_f32_16x16x32_bf16 v[110:113], v[152:155], v[192:195], v[110:113]
	v_mfma_f32_16x16x32_bf16 v[106:109], v[160:163], v[192:195], v[106:109]
	v_mfma_f32_16x16x32_bf16 v[94:97], v[152:155], v[214:217], v[94:97]
	v_mfma_f32_16x16x32_bf16 v[90:93], v[160:163], v[214:217], v[90:93]
	v_mfma_f32_16x16x32_bf16 v[78:81], v[152:155], v[222:225], v[78:81]
	v_mfma_f32_16x16x32_bf16 v[74:77], v[160:163], v[222:225], v[74:77]
	v_mfma_f32_16x16x32_bf16 v[118:121], v[164:167], v[180:183], v[118:121]
	v_mfma_f32_16x16x32_bf16 v[114:117], v[172:175], v[180:183], v[114:117]
	v_mfma_f32_16x16x32_bf16 v[102:105], v[164:167], v[188:191], v[102:105]
	v_mfma_f32_16x16x32_bf16 v[98:101], v[172:175], v[188:191], v[98:101]
	v_mfma_f32_16x16x32_bf16 v[86:89], v[164:167], v[210:213], v[86:89]
	v_mfma_f32_16x16x32_bf16 v[82:85], v[172:175], v[210:213], v[82:85]
	v_mfma_f32_16x16x32_bf16 v[70:73], v[164:167], v[218:221], v[70:73]
	v_mfma_f32_16x16x32_bf16 v[66:69], v[172:175], v[218:221], v[66:69]
	v_mfma_f32_16x16x32_bf16 v[118:121], v[168:171], v[184:187], v[118:121]
	v_mfma_f32_16x16x32_bf16 v[114:117], v[176:179], v[184:187], v[114:117]
	v_mfma_f32_16x16x32_bf16 v[102:105], v[168:171], v[192:195], v[102:105]
	v_mfma_f32_16x16x32_bf16 v[98:101], v[176:179], v[192:195], v[98:101]
	v_mfma_f32_16x16x32_bf16 v[86:89], v[168:171], v[214:217], v[86:89]
	v_mfma_f32_16x16x32_bf16 v[82:85], v[176:179], v[214:217], v[82:85]
	v_mfma_f32_16x16x32_bf16 v[70:73], v[168:171], v[222:225], v[70:73]
	v_mfma_f32_16x16x32_bf16 v[66:69], v[176:179], v[222:225], v[66:69]
	s_barrier
	s_add_i32 s28, s68, s30
	v_lshl_add_u64 v[142:143], v[142:143], 0, s[42:43]
	s_mov_b32 m0, s28
	ds_read_b128 v[180:183], v146 offset:49152
	ds_read_b128 v[184:187], v146 offset:50176
	ds_read_b128 v[188:191], v146 offset:51200
	ds_read_b128 v[192:195], v146 offset:52224
	ds_read_b128 v[210:213], v146 offset:53248
	ds_read_b128 v[214:217], v146 offset:54272
	ds_read_b128 v[218:221], v146 offset:55296
	ds_read_b128 v[222:225], v146 offset:56320
	global_load_lds_dwordx4 v[142:143], off
	s_add_i32 m0, s28, 0x2000
	s_add_u32 s26, s26, 0x80080
	v_lshl_add_u64 v[142:143], v[240:241], 0, s[42:43]
	s_addc_u32 s27, s27, 0
	s_add_i32 s28, s69, s30
	global_load_lds_dwordx4 v[142:143], off
	v_lshl_add_u64 v[142:143], s[26:27], 0, v[0:1]
	s_mov_b32 m0, s28
	s_nop 0
	global_load_lds_dwordx4 v[142:143], off
	v_lshl_add_u64 v[142:143], s[26:27], 0, v[130:131]
	s_add_i32 m0, s28, 0x2000
	s_nop 0
	global_load_lds_dwordx4 v[142:143], off
	s_waitcnt vmcnt(4)
	s_waitcnt lgkmcnt(0)
	s_barrier
	v_mfma_f32_16x16x32_bf16 v[62:65], v[148:151], v[180:183], v[62:65]
	v_mfma_f32_16x16x32_bf16 v[58:61], v[156:159], v[180:183], v[58:61]
	v_mfma_f32_16x16x32_bf16 v[46:49], v[148:151], v[188:191], v[46:49]
	v_mfma_f32_16x16x32_bf16 v[42:45], v[156:159], v[188:191], v[42:45]
	v_mfma_f32_16x16x32_bf16 v[30:33], v[148:151], v[210:213], v[30:33]
	v_mfma_f32_16x16x32_bf16 v[26:29], v[156:159], v[210:213], v[26:29]
	v_mfma_f32_16x16x32_bf16 v[14:17], v[148:151], v[218:221], v[14:17]
	v_mfma_f32_16x16x32_bf16 v[10:13], v[156:159], v[218:221], v[10:13]
	v_mfma_f32_16x16x32_bf16 v[62:65], v[152:155], v[184:187], v[62:65]
	v_mfma_f32_16x16x32_bf16 v[58:61], v[160:163], v[184:187], v[58:61]
	v_mfma_f32_16x16x32_bf16 v[46:49], v[152:155], v[192:195], v[46:49]
	v_mfma_f32_16x16x32_bf16 v[42:45], v[160:163], v[192:195], v[42:45]
	v_mfma_f32_16x16x32_bf16 v[30:33], v[152:155], v[214:217], v[30:33]
	v_mfma_f32_16x16x32_bf16 v[26:29], v[160:163], v[214:217], v[26:29]
	v_mfma_f32_16x16x32_bf16 v[14:17], v[152:155], v[222:225], v[14:17]
	v_mfma_f32_16x16x32_bf16 v[10:13], v[160:163], v[222:225], v[10:13]
	v_mfma_f32_16x16x32_bf16 v[54:57], v[164:167], v[180:183], v[54:57]
	v_mfma_f32_16x16x32_bf16 v[50:53], v[172:175], v[180:183], v[50:53]
	v_mfma_f32_16x16x32_bf16 v[38:41], v[164:167], v[188:191], v[38:41]
	v_mfma_f32_16x16x32_bf16 v[34:37], v[172:175], v[188:191], v[34:37]
	v_mfma_f32_16x16x32_bf16 v[22:25], v[164:167], v[210:213], v[22:25]
	v_mfma_f32_16x16x32_bf16 v[18:21], v[172:175], v[210:213], v[18:21]
	v_mfma_f32_16x16x32_bf16 v[6:9], v[164:167], v[218:221], v[6:9]
	v_mfma_f32_16x16x32_bf16 v[2:5], v[172:175], v[218:221], v[2:5]
	v_mfma_f32_16x16x32_bf16 v[54:57], v[168:171], v[184:187], v[54:57]
	v_mfma_f32_16x16x32_bf16 v[50:53], v[176:179], v[184:187], v[50:53]
	v_mfma_f32_16x16x32_bf16 v[38:41], v[168:171], v[192:195], v[38:41]
	v_mfma_f32_16x16x32_bf16 v[34:37], v[176:179], v[192:195], v[34:37]
	v_mfma_f32_16x16x32_bf16 v[22:25], v[168:171], v[214:217], v[22:25]
	v_mfma_f32_16x16x32_bf16 v[18:21], v[176:179], v[214:217], v[18:21]
	v_mfma_f32_16x16x32_bf16 v[6:9], v[168:171], v[222:225], v[6:9]
	v_mfma_f32_16x16x32_bf16 v[2:5], v[176:179], v[222:225], v[2:5]
	s_barrier
	s_add_i32 s67, s67, 2
	s_add_u32 s15, s15, 0x100
	s_addc_u32 s17, s17, 0
	s_add_u32 s24, s24, 0x100
	s_addc_u32 s25, s25, 0
	s_cmp_gt_u32 s67, 29
	s_cbranch_scc0 .LBB0_143
	s_and_b64 vcc, exec, s[12:13]
	s_cbranch_vccz .LBB0_146
	s_barrier
	s_setprio 1

; #define PG8_STAGE(bufoff, gbase, voff) do { _Pragma("unroll") for (int _i = 0; _i < 2; ++_i) \
;         __builtin_amdgcn_global_load_lds((const unsigned*)((const char*)(gbase) + (voff)[_i]), (LAS unsigned*)(lds + (bufoff) + ldsw + _i * 8192), 16, 0, 0); } while (0)
; #define PG8_LDA(dst, b, h) do { _Pragma("unroll") for (int m = 0; m < 4; ++m) _Pragma("unroll") for (int k = 0; k < 2; ++k) dst[m][k] = *(const LAS bf16x8*)(lds + PG8_SA(b, h) + aoff + m * 2048 + k * 1024); } while (0)
; #define PG8_LDB(dst, b, h) do { _Pragma("unroll") for (int n = 0; n < 2; ++n) _Pragma("unroll") for (int k = 0; k < 2; ++k) dst[n][k] = *(const LAS bf16x8*)(lds + PG8_SB(b, h) + boff + n * 2048 + k * 1024); } while (0)
; #define PG8_WAIT_V(n) asm volatile("s_waitcnt vmcnt(" #n ")" ::: "memory")
; #define PG8_WAIT_L(n) asm volatile("s_waitcnt lgkmcnt(" #n ")" ::: "memory")
; #define PG8_BAR __builtin_amdgcn_s_barrier()
; template <class Epi, bool ALIGN_EPI>
; __device__ __forceinline__ void gemm_phase(LAS unsigned char* lds, const int tid, const Gemm g, const StaticOrder& S, const Epi& E) {
;     ...
;         const bool has_next = S.next(ui + 1, nxt);
;         const char* nA = has_next ? (const char*)g.A + (size_t)nxt.pm * tstepA + PG8_KOFFA(nxt) : cA; const char* nB = has_next ? (const char*)g.Bt + (size_t)nxt.pn * tstepB + PG8_KOFFB(nxt) : cB;
;         const int nt = cur.ks >= 0 ? nt_split : nt_full;
;         for (int t = 0; t < nt; t += 2) {
;             if constexpr (Epi::HOOK) { if (t != 0 && (t & 7) == 0) E.hook(acc, cur, (t >> 3) - 1, wr, wc, fr, fq); }
;             const bool last = (t == nt - 2);
;             const char* a1 = cA + (size_t)(t + 1) * kstepA;
;             const char* a2 = last ? nA : cA + (size_t)(t + 2) * kstepA; const char* b2 = last ? nB : cB + (size_t)(t + 2) * kstepB;
;             const char* a3 = a2 + kstepA; const char* b3 = b2 + kstepB;
;             PG8_LDB(B0, 0, 0); PG8_LDB(B1, 0, 1); PG8_SCHED; PG8_LDA(At, 0, 0); PG8_STAGE(PG8_SA(1, 1), a1 + hstepA, voffA);
;             PG8_WAIT_V(8); PG8_WAIT_L(0); PG8_BAR; PG8_MMA(0, 0, At, B0); PG8_MMA(0, 1, At, B1); PG8_BAR; PG8_SCHED;
;             PG8_LDA(At, 0, 1); PG8_STAGE(PG8_SB(0, 0), b2, voffB); PG8_STAGE(PG8_SB(0, 1), b2 + hstepB, voffB); PG8_STAGE(PG8_SA(0, 0), a2, voffA);
;             PG8_WAIT_V(8); PG8_WAIT_L(0); PG8_BAR; PG8_MMA(1, 0, At, B0); PG8_MMA(1, 1, At, B1); PG8_BAR; PG8_SCHED;
.LBB0_209:
	s_setprio 0
	s_add_i32 s72, s34, 2
	s_add_u32 s35, s30, 0xfff80080
	s_addc_u32 s54, s31, -1
	s_cmp_eq_u32 s21, s34
	s_cselect_b32 s55, s23, s54
	s_cselect_b32 s54, s22, s35
	s_cselect_b32 s35, s25, s71
	s_cselect_b32 s34, s24, s27
	s_add_i32 s73, 0, 0x10000
	s_add_i32 s85, 0, 0x14000
	v_add_u32_e32 v148, s73, v175
	v_add_u32_e32 v164, s85, v175
	ds_read_b128 v[136:139], v148
	ds_read_b128 v[140:143], v148 offset:1024
	ds_read_b128 v[144:147], v148 offset:2048
	ds_read_b128 v[148:151], v148 offset:3072
	ds_read_b128 v[152:155], v164
	ds_read_b128 v[156:159], v164 offset:1024
	ds_read_b128 v[160:163], v164 offset:2048
	ds_read_b128 v[164:167], v164 offset:3072
	v_lshl_add_u64 v[172:173], s[30:31], 0, v[134:135]
	s_add_i32 m0, s58, 0xc000
	ds_read_b128 v[168:171], v177
	ds_read_b128 v[178:181], v177 offset:1024
	ds_read_b128 v[182:185], v177 offset:2048
	ds_read_b128 v[186:189], v177 offset:3072
	ds_read_b128 v[190:193], v177 offset:4096
	ds_read_b128 v[210:213], v177 offset:5120
	ds_read_b128 v[214:217], v177 offset:6144
	ds_read_b128 v[218:221], v177 offset:7168
	global_load_lds_dwordx4 v[172:173], off
	v_lshl_add_u64 v[172:173], s[30:31], 0, v[132:133]
	s_add_i32 m0, s58, 0xe000
	s_nop 0
	global_load_lds_dwordx4 v[172:173], off
	s_sub_u32 s98, s30, 0x80000
	s_subb_u32 s99, s31, 0
	v_lshl_add_u64 v[172:173], s[98:99], 0, v[134:135]
	s_mov_b32 m0, s65
	s_nop 0
	global_load_lds_dwordx4 v[172:173], off
	v_lshl_add_u64 v[172:173], s[98:99], 0, v[132:133]
	s_mov_b32 m0, s66
	s_nop 0
	global_load_lds_dwordx4 v[172:173], off
	s_waitcnt vmcnt(8)
	s_waitcnt lgkmcnt(0)
	s_barrier
	v_mfma_f32_16x16x32_bf16 v[126:129], v[136:139], v[168:171], v[126:129]
	v_mfma_f32_16x16x32_bf16 v[94:97], v[144:147], v[168:171], v[94:97]
	v_mfma_f32_16x16x32_bf16 v[122:125], v[136:139], v[182:185], v[122:125]
	v_mfma_f32_16x16x32_bf16 v[90:93], v[144:147], v[182:185], v[90:93]
	v_mfma_f32_16x16x32_bf16 v[118:121], v[136:139], v[190:193], v[118:121]
	v_mfma_f32_16x16x32_bf16 v[86:89], v[144:147], v[190:193], v[86:89]
	v_mfma_f32_16x16x32_bf16 v[114:117], v[136:139], v[214:217], v[114:117]
	v_mfma_f32_16x16x32_bf16 v[82:85], v[144:147], v[214:217], v[82:85]
	v_mfma_f32_16x16x32_bf16 v[126:129], v[140:143], v[178:181], v[126:129]
	v_mfma_f32_16x16x32_bf16 v[94:97], v[148:151], v[178:181], v[94:97]
	v_mfma_f32_16x16x32_bf16 v[122:125], v[140:143], v[186:189], v[122:125]
	v_mfma_f32_16x16x32_bf16 v[90:93], v[148:151], v[186:189], v[90:93]
	v_mfma_f32_16x16x32_bf16 v[118:121], v[140:143], v[210:213], v[118:121]
	v_mfma_f32_16x16x32_bf16 v[86:89], v[148:151], v[210:213], v[86:89]
	v_mfma_f32_16x16x32_bf16 v[114:117], v[140:143], v[218:221], v[114:117]
	v_mfma_f32_16x16x32_bf16 v[82:85], v[148:151], v[218:221], v[82:85]
	v_mfma_f32_16x16x32_bf16 v[62:65], v[152:155], v[168:171], v[62:65]
	v_mfma_f32_16x16x32_bf16 v[42:45], v[160:163], v[168:171], v[42:45]
	v_mfma_f32_16x16x32_bf16 v[58:61], v[152:155], v[182:185], v[58:61]
	v_mfma_f32_16x16x32_bf16 v[34:37], v[160:163], v[182:185], v[34:37]
	v_mfma_f32_16x16x32_bf16 v[54:57], v[152:155], v[190:193], v[54:57]
	v_mfma_f32_16x16x32_bf16 v[26:29], v[160:163], v[190:193], v[26:29]
	v_mfma_f32_16x16x32_bf16 v[50:53], v[152:155], v[214:217], v[50:53]
	v_mfma_f32_16x16x32_bf16 v[18:21], v[160:163], v[214:217], v[18:21]
	v_mfma_f32_16x16x32_bf16 v[62:65], v[156:159], v[178:181], v[62:65]
	v_mfma_f32_16x16x32_bf16 v[42:45], v[164:167], v[178:181], v[42:45]
	v_mfma_f32_16x16x32_bf16 v[58:61], v[156:159], v[186:189], v[58:61]
	v_mfma_f32_16x16x32_bf16 v[34:37], v[164:167], v[186:189], v[34:37]
	v_mfma_f32_16x16x32_bf16 v[54:57], v[156:159], v[210:213], v[54:57]
	v_mfma_f32_16x16x32_bf16 v[26:29], v[164:167], v[210:213], v[26:29]
	v_mfma_f32_16x16x32_bf16 v[50:53], v[156:159], v[218:221], v[50:53]
	v_mfma_f32_16x16x32_bf16 v[18:21], v[164:167], v[218:221], v[18:21]
	s_barrier
	s_add_i32 s73, s73, s56
	v_lshl_add_u64 v[172:173], s[34:35], 0, v[0:1]
	s_mov_b32 m0, s73
	ds_read_b128 v[168:171], v177 offset:16384
	ds_read_b128 v[178:181], v177 offset:17408
	ds_read_b128 v[182:185], v177 offset:18432
	ds_read_b128 v[186:189], v177 offset:19456
	ds_read_b128 v[190:193], v177 offset:20480
	ds_read_b128 v[210:213], v177 offset:21504
	ds_read_b128 v[214:217], v177 offset:22528
	ds_read_b128 v[218:221], v177 offset:23552
	global_load_lds_dwordx4 v[172:173], off
	s_add_i32 m0, s73, 0x2000
	s_add_u32 s90, s34, 0x80000
	v_lshl_add_u64 v[194:195], s[34:35], 0, v[130:131]
	s_addc_u32 s91, s35, 0
	s_add_i32 s73, s85, s56
	global_load_lds_dwordx4 v[194:195], off
	v_lshl_add_u64 v[222:223], s[90:91], 0, v[0:1]
	s_mov_b32 m0, s73
	v_lshl_add_u64 v[224:225], s[54:55], 0, v[130:131]
	global_load_lds_dwordx4 v[222:223], off
	v_lshl_add_u64 v[222:223], s[90:91], 0, v[130:131]
	s_add_i32 m0, s73, 0x2000
	s_nop 0
	global_load_lds_dwordx4 v[222:223], off
	v_lshl_add_u64 v[222:223], s[54:55], 0, v[0:1]
	s_waitcnt vmcnt(4)
	s_waitcnt lgkmcnt(0)
	s_barrier
; #define PG8_STAGE(bufoff, gbase, voff) do { _Pragma("unroll") for (int _i = 0; _i < 2; ++_i) \
;         __builtin_amdgcn_global_load_lds((const unsigned*)((const char*)(gbase) + (voff)[_i]), (LAS unsigned*)(lds + (bufoff) + ldsw + _i * 8192), 16, 0, 0); } while (0)
; #define PG8_LDA(dst, b, h) do { _Pragma("unroll") for (int m = 0; m < 4; ++m) _Pragma("unroll") for (int k = 0; k < 2; ++k) dst[m][k] = *(const LAS bf16x8*)(lds + PG8_SA(b, h) + aoff + m * 2048 + k * 1024); } while (0)
; #define PG8_LDB(dst, b, h) do { _Pragma("unroll") for (int n = 0; n < 2; ++n) _Pragma("unroll") for (int k = 0; k < 2; ++k) dst[n][k] = *(const LAS bf16x8*)(lds + PG8_SB(b, h) + boff + n * 2048 + k * 1024); } while (0)
; #define PG8_MMA(ai, bj, At, Bt) do { __builtin_amdgcn_s_setprio(1); _Pragma("unroll") for (int m = 0; m < 4; ++m) _Pragma("unroll") for (int n = 0; n < 2; ++n) _Pragma("unroll") for (int k = 0; k < 2; ++k) \
;         acc[ai][bj][m][n] = __builtin_amdgcn_mfma_f32_16x16x32_bf16(Bt[n][k], At[m][k], acc[ai][bj][m][n], 0, 0, 0); __builtin_amdgcn_s_setprio(0); } while (0)
; #define PG8_WAIT_V(n) asm volatile("s_waitcnt vmcnt(" #n ")" ::: "memory")
; #define PG8_WAIT_L(n) asm volatile("s_waitcnt lgkmcnt(" #n ")" ::: "memory")
; #define PG8_BAR __builtin_amdgcn_s_barrier()
; #define PG8_SCHED __builtin_amdgcn_sched_barrier(0)
; template <class Epi, bool ALIGN_EPI>
; __device__ __forceinline__ void gemm_phase(LAS unsigned char* lds, const int tid, const Gemm g, const StaticOrder& S, const Epi& E) {
;     ...
;             PG8_WAIT_V(8); PG8_WAIT_L(0); PG8_BAR; PG8_MMA(1, 0, At, B0); PG8_MMA(1, 1, At, B1); PG8_BAR; PG8_SCHED;
;             PG8_LDB(B0, 1, 0); PG8_LDB(B1, 1, 1); PG8_SCHED; PG8_LDA(At, 1, 0); PG8_STAGE(PG8_SA(0, 1), a2 + hstepA, voffA);
;             PG8_WAIT_V(8); PG8_WAIT_L(0); PG8_BAR; PG8_MMA(0, 0, At, B0); PG8_MMA(0, 1, At, B1); PG8_BAR; PG8_SCHED;
	v_mfma_f32_16x16x32_bf16 v[110:113], v[136:139], v[168:171], v[110:113]
	v_mfma_f32_16x16x32_bf16 v[78:81], v[144:147], v[168:171], v[78:81]
	v_mfma_f32_16x16x32_bf16 v[106:109], v[136:139], v[182:185], v[106:109]
	v_mfma_f32_16x16x32_bf16 v[74:77], v[144:147], v[182:185], v[74:77]
	v_mfma_f32_16x16x32_bf16 v[102:105], v[136:139], v[190:193], v[102:105]
	v_mfma_f32_16x16x32_bf16 v[70:73], v[144:147], v[190:193], v[70:73]
	v_mfma_f32_16x16x32_bf16 v[98:101], v[136:139], v[214:217], v[98:101]
	v_mfma_f32_16x16x32_bf16 v[66:69], v[144:147], v[214:217], v[66:69]
	v_mfma_f32_16x16x32_bf16 v[110:113], v[140:143], v[178:181], v[110:113]
	v_mfma_f32_16x16x32_bf16 v[78:81], v[148:151], v[178:181], v[78:81]
	v_mfma_f32_16x16x32_bf16 v[106:109], v[140:143], v[186:189], v[106:109]
	v_mfma_f32_16x16x32_bf16 v[74:77], v[148:151], v[186:189], v[74:77]
	v_mfma_f32_16x16x32_bf16 v[102:105], v[140:143], v[210:213], v[102:105]
	v_mfma_f32_16x16x32_bf16 v[70:73], v[148:151], v[210:213], v[70:73]
	v_mfma_f32_16x16x32_bf16 v[98:101], v[140:143], v[218:221], v[98:101]
	v_mfma_f32_16x16x32_bf16 v[66:69], v[148:151], v[218:221], v[66:69]
	v_mfma_f32_16x16x32_bf16 v[46:49], v[152:155], v[168:171], v[46:49]
	v_mfma_f32_16x16x32_bf16 v[14:17], v[160:163], v[168:171], v[14:17]
	v_mfma_f32_16x16x32_bf16 v[38:41], v[152:155], v[182:185], v[38:41]
	v_mfma_f32_16x16x32_bf16 v[10:13], v[160:163], v[182:185], v[10:13]
	v_mfma_f32_16x16x32_bf16 v[30:33], v[152:155], v[190:193], v[30:33]
	v_mfma_f32_16x16x32_bf16 v[6:9], v[160:163], v[190:193], v[6:9]
	v_mfma_f32_16x16x32_bf16 v[22:25], v[152:155], v[214:217], v[22:25]
	v_mfma_f32_16x16x32_bf16 v[2:5], v[160:163], v[214:217], v[2:5]
	v_mfma_f32_16x16x32_bf16 v[46:49], v[156:159], v[178:181], v[46:49]
	v_mfma_f32_16x16x32_bf16 v[14:17], v[164:167], v[178:181], v[14:17]
	v_mfma_f32_16x16x32_bf16 v[38:41], v[156:159], v[186:189], v[38:41]
	v_mfma_f32_16x16x32_bf16 v[10:13], v[164:167], v[186:189], v[10:13]
	v_mfma_f32_16x16x32_bf16 v[30:33], v[156:159], v[210:213], v[30:33]
	v_mfma_f32_16x16x32_bf16 v[6:9], v[164:167], v[210:213], v[6:9]
	v_mfma_f32_16x16x32_bf16 v[22:25], v[156:159], v[218:221], v[22:25]
	v_mfma_f32_16x16x32_bf16 v[2:5], v[164:167], v[218:221], v[2:5]
	s_barrier
	s_add_i32 s73, 0, 0x18000
	s_add_i32 s85, 0, 0x1c000
	v_add_u32_e32 v148, s73, v175
	v_add_u32_e32 v164, s85, v175
	ds_read_b128 v[136:139], v148
	ds_read_b128 v[140:143], v148 offset:1024
	ds_read_b128 v[144:147], v148 offset:2048
	ds_read_b128 v[148:151], v148 offset:3072
	ds_read_b128 v[152:155], v164
	ds_read_b128 v[156:159], v164 offset:1024
	ds_read_b128 v[160:163], v164 offset:2048
	ds_read_b128 v[164:167], v164 offset:3072
	s_mov_b32 m0, s58
	s_nop 0
	global_load_lds_dwordx4 v[222:223], off
	s_mov_b32 m0, s60
	s_nop 0
	global_load_lds_dwordx4 v[224:225], off
	s_add_u32 s54, s54, 0x80000
	s_addc_u32 s55, s55, 0
	s_mov_b32 m0, s61
	v_lshl_add_u64 v[240:241], s[54:55], 0, v[0:1]
	ds_read_b128 v[168:171], v177 offset:32768
	ds_read_b128 v[178:181], v177 offset:33792
	ds_read_b128 v[182:185], v177 offset:34816
	ds_read_b128 v[186:189], v177 offset:35840
	ds_read_b128 v[190:193], v177 offset:36864
	ds_read_b128 v[210:213], v177 offset:37888
	ds_read_b128 v[214:217], v177 offset:38912
	ds_read_b128 v[218:221], v177 offset:39936
	global_load_lds_dwordx4 v[240:241], off
	v_lshl_add_u64 v[240:241], s[54:55], 0, v[130:131]
	s_mov_b32 m0, s62
	s_nop 0
	global_load_lds_dwordx4 v[240:241], off
	s_waitcnt vmcnt(8)
	s_waitcnt lgkmcnt(0)
	s_barrier
; #define PG8_STAGE(bufoff, gbase, voff) do { _Pragma("unroll") for (int _i = 0; _i < 2; ++_i) \
;         __builtin_amdgcn_global_load_lds((const unsigned*)((const char*)(gbase) + (voff)[_i]), (LAS unsigned*)(lds + (bufoff) + ldsw + _i * 8192), 16, 0, 0); } while (0)
; #define PG8_LDA(dst, b, h) do { _Pragma("unroll") for (int m = 0; m < 4; ++m) _Pragma("unroll") for (int k = 0; k < 2; ++k) dst[m][k] = *(const LAS bf16x8*)(lds + PG8_SA(b, h) + aoff + m * 2048 + k * 1024); } while (0)
; #define PG8_MMA(ai, bj, At, Bt) do { __builtin_amdgcn_s_setprio(1); _Pragma("unroll") for (int m = 0; m < 4; ++m) _Pragma("unroll") for (int n = 0; n < 2; ++n) _Pragma("unroll") for (int k = 0; k < 2; ++k) \
;         acc[ai][bj][m][n] = __builtin_amdgcn_mfma_f32_16x16x32_bf16(Bt[n][k], At[m][k], acc[ai][bj][m][n], 0, 0, 0); __builtin_amdgcn_s_setprio(0); } while (0)
; #define PG8_WAIT_V(n) asm volatile("s_waitcnt vmcnt(" #n ")" ::: "memory")
; #define PG8_WAIT_L(n) asm volatile("s_waitcnt lgkmcnt(" #n ")" ::: "memory")
; #define PG8_BAR __builtin_amdgcn_s_barrier()
; #define PG8_SCHED __builtin_amdgcn_sched_barrier(0)
; template <class Epi, bool ALIGN_EPI>
; __device__ __forceinline__ void gemm_phase(LAS unsigned char* lds, const int tid, const Gemm g, const StaticOrder& S, const Epi& E) {
;     ...
;             PG8_WAIT_V(8); PG8_WAIT_L(0); PG8_BAR; PG8_MMA(0, 0, At, B0); PG8_MMA(0, 1, At, B1); PG8_BAR; PG8_SCHED;
;             PG8_LDA(At, 1, 1); PG8_STAGE(PG8_SB(1, 0), b3, voffB); PG8_STAGE(PG8_SB(1, 1), b3 + hstepB, voffB); PG8_STAGE(PG8_SA(1, 0), a3, voffA);
;             PG8_WAIT_V(8); PG8_WAIT_L(0); PG8_BAR; PG8_MMA(1, 0, At, B0); PG8_MMA(1, 1, At, B1); PG8_BAR; PG8_SCHED;
;         }
;         if constexpr (ALIGN_EPI) { if (wr == 0) PG8_BAR; }
;         E(acc, cur, wr, wc, fr, fq);
	v_mfma_f32_16x16x32_bf16 v[126:129], v[136:139], v[168:171], v[126:129]
	v_mfma_f32_16x16x32_bf16 v[94:97], v[144:147], v[168:171], v[94:97]
	v_mfma_f32_16x16x32_bf16 v[122:125], v[136:139], v[182:185], v[122:125]
	v_mfma_f32_16x16x32_bf16 v[90:93], v[144:147], v[182:185], v[90:93]
	v_mfma_f32_16x16x32_bf16 v[118:121], v[136:139], v[190:193], v[118:121]
	v_mfma_f32_16x16x32_bf16 v[86:89], v[144:147], v[190:193], v[86:89]
	v_mfma_f32_16x16x32_bf16 v[114:117], v[136:139], v[214:217], v[114:117]
	v_mfma_f32_16x16x32_bf16 v[82:85], v[144:147], v[214:217], v[82:85]
	v_mfma_f32_16x16x32_bf16 v[126:129], v[140:143], v[178:181], v[126:129]
	v_mfma_f32_16x16x32_bf16 v[94:97], v[148:151], v[178:181], v[94:97]
	v_mfma_f32_16x16x32_bf16 v[122:125], v[140:143], v[186:189], v[122:125]
	v_mfma_f32_16x16x32_bf16 v[90:93], v[148:151], v[186:189], v[90:93]
	v_mfma_f32_16x16x32_bf16 v[118:121], v[140:143], v[210:213], v[118:121]
	v_mfma_f32_16x16x32_bf16 v[86:89], v[148:151], v[210:213], v[86:89]
	v_mfma_f32_16x16x32_bf16 v[114:117], v[140:143], v[218:221], v[114:117]
	v_mfma_f32_16x16x32_bf16 v[82:85], v[148:151], v[218:221], v[82:85]
	v_mfma_f32_16x16x32_bf16 v[62:65], v[152:155], v[168:171], v[62:65]
	v_mfma_f32_16x16x32_bf16 v[42:45], v[160:163], v[168:171], v[42:45]
	v_mfma_f32_16x16x32_bf16 v[58:61], v[152:155], v[182:185], v[58:61]
	v_mfma_f32_16x16x32_bf16 v[34:37], v[160:163], v[182:185], v[34:37]
	v_mfma_f32_16x16x32_bf16 v[54:57], v[152:155], v[190:193], v[54:57]
	v_mfma_f32_16x16x32_bf16 v[26:29], v[160:163], v[190:193], v[26:29]
	v_mfma_f32_16x16x32_bf16 v[50:53], v[152:155], v[214:217], v[50:53]
	v_mfma_f32_16x16x32_bf16 v[18:21], v[160:163], v[214:217], v[18:21]
	v_mfma_f32_16x16x32_bf16 v[62:65], v[156:159], v[178:181], v[62:65]
	v_mfma_f32_16x16x32_bf16 v[42:45], v[164:167], v[178:181], v[42:45]
	v_mfma_f32_16x16x32_bf16 v[58:61], v[156:159], v[186:189], v[58:61]
	v_mfma_f32_16x16x32_bf16 v[34:37], v[164:167], v[186:189], v[34:37]
	v_mfma_f32_16x16x32_bf16 v[54:57], v[156:159], v[210:213], v[54:57]
	v_mfma_f32_16x16x32_bf16 v[26:29], v[164:167], v[210:213], v[26:29]
	v_mfma_f32_16x16x32_bf16 v[50:53], v[156:159], v[218:221], v[50:53]
	v_mfma_f32_16x16x32_bf16 v[18:21], v[164:167], v[218:221], v[18:21]
	s_barrier
	s_add_i32 s54, s73, s56
	v_lshl_add_u64 v[172:173], v[172:173], 0, s[42:43]
	s_mov_b32 m0, s54
	ds_read_b128 v[168:171], v177 offset:49152
	ds_read_b128 v[178:181], v177 offset:50176
	ds_read_b128 v[182:185], v177 offset:51200
	ds_read_b128 v[186:189], v177 offset:52224
	ds_read_b128 v[190:193], v177 offset:53248
	ds_read_b128 v[210:213], v177 offset:54272
	ds_read_b128 v[214:217], v177 offset:55296
	ds_read_b128 v[218:221], v177 offset:56320
	global_load_lds_dwordx4 v[172:173], off
	s_add_i32 m0, s54, 0x2000
	s_add_u32 s34, s34, 0x80080
	v_lshl_add_u64 v[172:173], v[194:195], 0, s[42:43]
	s_addc_u32 s35, s35, 0
	s_add_i32 s54, s85, s56
	global_load_lds_dwordx4 v[172:173], off
	v_lshl_add_u64 v[172:173], s[34:35], 0, v[0:1]
	s_mov_b32 m0, s54
	s_nop 0
	global_load_lds_dwordx4 v[172:173], off
	v_lshl_add_u64 v[172:173], s[34:35], 0, v[130:131]
	s_add_i32 m0, s54, 0x2000
	s_nop 0
	global_load_lds_dwordx4 v[172:173], off
	s_waitcnt vmcnt(4)
	s_waitcnt lgkmcnt(0)
	s_barrier
	v_mfma_f32_16x16x32_bf16 v[110:113], v[136:139], v[168:171], v[110:113]
	v_mfma_f32_16x16x32_bf16 v[78:81], v[144:147], v[168:171], v[78:81]
	v_mfma_f32_16x16x32_bf16 v[106:109], v[136:139], v[182:185], v[106:109]
	v_mfma_f32_16x16x32_bf16 v[74:77], v[144:147], v[182:185], v[74:77]
	v_mfma_f32_16x16x32_bf16 v[102:105], v[136:139], v[190:193], v[102:105]
	v_mfma_f32_16x16x32_bf16 v[70:73], v[144:147], v[190:193], v[70:73]
	v_mfma_f32_16x16x32_bf16 v[98:101], v[136:139], v[214:217], v[98:101]
	v_mfma_f32_16x16x32_bf16 v[66:69], v[144:147], v[214:217], v[66:69]
	v_mfma_f32_16x16x32_bf16 v[110:113], v[140:143], v[178:181], v[110:113]
	v_mfma_f32_16x16x32_bf16 v[78:81], v[148:151], v[178:181], v[78:81]
	v_mfma_f32_16x16x32_bf16 v[106:109], v[140:143], v[186:189], v[106:109]
	v_mfma_f32_16x16x32_bf16 v[74:77], v[148:151], v[186:189], v[74:77]
	v_mfma_f32_16x16x32_bf16 v[102:105], v[140:143], v[210:213], v[102:105]
	v_mfma_f32_16x16x32_bf16 v[70:73], v[148:151], v[210:213], v[70:73]
	v_mfma_f32_16x16x32_bf16 v[98:101], v[140:143], v[218:221], v[98:101]
	v_mfma_f32_16x16x32_bf16 v[66:69], v[148:151], v[218:221], v[66:69]
	v_mfma_f32_16x16x32_bf16 v[46:49], v[152:155], v[168:171], v[46:49]
	v_mfma_f32_16x16x32_bf16 v[14:17], v[160:163], v[168:171], v[14:17]
	v_mfma_f32_16x16x32_bf16 v[38:41], v[152:155], v[182:185], v[38:41]
	v_mfma_f32_16x16x32_bf16 v[10:13], v[160:163], v[182:185], v[10:13]
	v_mfma_f32_16x16x32_bf16 v[30:33], v[152:155], v[190:193], v[30:33]
	v_mfma_f32_16x16x32_bf16 v[6:9], v[160:163], v[190:193], v[6:9]
	v_mfma_f32_16x16x32_bf16 v[22:25], v[152:155], v[214:217], v[22:25]
	v_mfma_f32_16x16x32_bf16 v[2:5], v[160:163], v[214:217], v[2:5]
	v_mfma_f32_16x16x32_bf16 v[46:49], v[156:159], v[178:181], v[46:49]
	v_mfma_f32_16x16x32_bf16 v[14:17], v[164:167], v[178:181], v[14:17]
	v_mfma_f32_16x16x32_bf16 v[38:41], v[156:159], v[186:189], v[38:41]
	v_mfma_f32_16x16x32_bf16 v[10:13], v[164:167], v[186:189], v[10:13]
	v_mfma_f32_16x16x32_bf16 v[30:33], v[156:159], v[210:213], v[30:33]
	v_mfma_f32_16x16x32_bf16 v[6:9], v[164:167], v[210:213], v[6:9]
	v_mfma_f32_16x16x32_bf16 v[22:25], v[156:159], v[218:221], v[22:25]
	v_mfma_f32_16x16x32_bf16 v[2:5], v[164:167], v[218:221], v[2:5]
	s_barrier
	s_add_u32 s27, s27, 0x100
	s_addc_u32 s71, s71, 0
	s_add_u32 s30, s30, 0x100
	s_addc_u32 s31, s31, 0
	s_cmp_ge_u32 s72, s19
	s_mov_b32 s34, s72
	s_cbranch_scc0 .LBB0_209
	s_and_b64 vcc, exec, s[16:17]
	s_cbranch_vccz .LBB0_212
	s_barrier
	s_setprio 1

; #define PG8_STAGE(bufoff, gbase, voff) do { _Pragma("unroll") for (int _i = 0; _i < 2; ++_i) \
;         __builtin_amdgcn_global_load_lds((const unsigned*)((const char*)(gbase) + (voff)[_i]), (LAS unsigned*)(lds + (bufoff) + ldsw + _i * 8192), 16, 0, 0); } while (0)
; #define PG8_LDA(dst, b, h) do { _Pragma("unroll") for (int m = 0; m < 4; ++m) _Pragma("unroll") for (int k = 0; k < 2; ++k) dst[m][k] = *(const LAS bf16x8*)(lds + PG8_SA(b, h) + aoff + m * 2048 + k * 1024); } while (0)
; #define PG8_LDB(dst, b, h) do { _Pragma("unroll") for (int n = 0; n < 2; ++n) _Pragma("unroll") for (int k = 0; k < 2; ++k) dst[n][k] = *(const LAS bf16x8*)(lds + PG8_SB(b, h) + boff + n * 2048 + k * 1024); } while (0)
; #define PG8_WAIT_V(n) asm volatile("s_waitcnt vmcnt(" #n ")" ::: "memory")
; #define PG8_WAIT_L(n) asm volatile("s_waitcnt lgkmcnt(" #n ")" ::: "memory")
; template <class Epi, bool ALIGN_EPI>
; __device__ __forceinline__ void gemm_phase(LAS unsigned char* lds, const int tid, const Gemm g, const StaticOrder& S, const Epi& E) {
;     ...
;     for (;;) {
;         const bool has_next = S.next(ui + 1, nxt);
;         const char* nA = has_next ? (const char*)g.A + (size_t)nxt.pm * tstepA + PG8_KOFFA(nxt) : cA; const char* nB = has_next ? (const char*)g.Bt + (size_t)nxt.pn * tstepB + PG8_KOFFB(nxt) : cB;
;         const int nt = cur.ks >= 0 ? nt_split : nt_full;
;         for (int t = 0; t < nt; t += 2) {
;             if constexpr (Epi::HOOK) { if (t != 0 && (t & 7) == 0) E.hook(acc, cur, (t >> 3) - 1, wr, wc, fr, fq); }
;             const bool last = (t == nt - 2);
;             const char* a1 = cA + (size_t)(t + 1) * kstepA;
;             const char* a2 = last ? nA : cA + (size_t)(t + 2) * kstepA; const char* b2 = last ? nB : cB + (size_t)(t + 2) * kstepB;
;             const char* a3 = a2 + kstepA; const char* b3 = b2 + kstepB;
;             PG8_LDB(B0, 0, 0); PG8_LDB(B1, 0, 1); PG8_SCHED; PG8_LDA(At, 0, 0); PG8_STAGE(PG8_SA(1, 1), a1 + hstepA, voffA);
;             PG8_WAIT_V(8); PG8_WAIT_L(0); PG8_BAR; PG8_MMA(0, 0, At, B0); PG8_MMA(0, 1, At, B1); PG8_BAR; PG8_SCHED;
;             PG8_LDA(At, 0, 1); PG8_STAGE(PG8_SB(0, 0), b2, voffB); PG8_STAGE(PG8_SB(0, 1), b2 + hstepB, voffB); PG8_STAGE(PG8_SA(0, 0), a2, voffA);
;             PG8_WAIT_V(8); PG8_WAIT_L(0); PG8_BAR; PG8_MMA(1, 0, At, B0); PG8_MMA(1, 1, At, B1); PG8_BAR; PG8_SCHED;
.LBB0_263:
	s_setprio 0
	s_add_i32 s5, s5, 2
	s_add_u32 s34, s30, 0xfff80080
	s_addc_u32 s35, s31, -1
	s_add_i32 s94, 0, 0x10000
	s_cmp_eq_u32 s91, s92
	s_cselect_b32 s55, s23, s35
	s_cselect_b32 s54, s22, s34
	v_add_u32_e32 v0, s94, v205
	s_cselect_b32 s35, s25, s36
	s_cselect_b32 s34, s24, s21
	s_add_i32 s96, 0, 0x14000
	ds_read_b128 v[132:135], v0
	ds_read_b128 v[136:139], v0 offset:1024
	ds_read_b128 v[140:143], v0 offset:2048
	ds_read_b128 v[144:147], v0 offset:3072
	v_add_u32_e32 v0, s96, v205
	ds_read_b128 v[148:151], v0
	ds_read_b128 v[152:155], v0 offset:1024
	ds_read_b128 v[156:159], v0 offset:2048
	ds_read_b128 v[160:163], v0 offset:3072
	v_lshl_add_u64 v[2:3], s[30:31], 0, v[220:221]
	s_add_i32 m0, s68, 0xc000
	ds_read_b128 v[164:167], v209
	ds_read_b128 v[168:171], v209 offset:1024
	ds_read_b128 v[172:175], v209 offset:2048
	ds_read_b128 v[176:179], v209 offset:3072
	ds_read_b128 v[180:183], v209 offset:4096
	ds_read_b128 v[184:187], v209 offset:5120
	ds_read_b128 v[188:191], v209 offset:6144
	ds_read_b128 v[192:195], v209 offset:7168
	global_load_lds_dwordx4 v[2:3], off
	v_lshl_add_u64 v[2:3], s[30:31], 0, v[218:219]
	s_add_i32 m0, s68, 0xe000
	s_nop 0
	global_load_lds_dwordx4 v[2:3], off
	s_sub_u32 s98, s30, 0x80000
	s_subb_u32 s99, s31, 0
	v_lshl_add_u64 v[2:3], s[98:99], 0, v[220:221]
	s_mov_b32 m0, s72
	s_nop 0
	global_load_lds_dwordx4 v[2:3], off
	v_lshl_add_u64 v[2:3], s[98:99], 0, v[218:219]
	s_mov_b32 m0, s73
	s_nop 0
	global_load_lds_dwordx4 v[2:3], off
	s_waitcnt vmcnt(8)
	s_waitcnt lgkmcnt(0)
	s_barrier
	v_mfma_f32_16x16x32_bf16 v[128:131], v[132:135], v[164:167], v[128:131]
	v_mfma_f32_16x16x32_bf16 v[124:127], v[140:143], v[164:167], v[124:127]
	v_mfma_f32_16x16x32_bf16 v[112:115], v[132:135], v[172:175], v[112:115]
	v_mfma_f32_16x16x32_bf16 v[108:111], v[140:143], v[172:175], v[108:111]
	v_mfma_f32_16x16x32_bf16 v[96:99], v[132:135], v[180:183], v[96:99]
	v_mfma_f32_16x16x32_bf16 v[92:95], v[140:143], v[180:183], v[92:95]
	v_mfma_f32_16x16x32_bf16 v[80:83], v[132:135], v[188:191], v[80:83]
	v_mfma_f32_16x16x32_bf16 v[76:79], v[140:143], v[188:191], v[76:79]
	v_mfma_f32_16x16x32_bf16 v[128:131], v[136:139], v[168:171], v[128:131]
	v_mfma_f32_16x16x32_bf16 v[124:127], v[144:147], v[168:171], v[124:127]
	v_mfma_f32_16x16x32_bf16 v[112:115], v[136:139], v[176:179], v[112:115]
	v_mfma_f32_16x16x32_bf16 v[108:111], v[144:147], v[176:179], v[108:111]
	v_mfma_f32_16x16x32_bf16 v[96:99], v[136:139], v[184:187], v[96:99]
	v_mfma_f32_16x16x32_bf16 v[92:95], v[144:147], v[184:187], v[92:95]
	v_mfma_f32_16x16x32_bf16 v[80:83], v[136:139], v[192:195], v[80:83]
	v_mfma_f32_16x16x32_bf16 v[76:79], v[144:147], v[192:195], v[76:79]
	v_mfma_f32_16x16x32_bf16 v[120:123], v[148:151], v[164:167], v[120:123]
	v_mfma_f32_16x16x32_bf16 v[116:119], v[156:159], v[164:167], v[116:119]
	v_mfma_f32_16x16x32_bf16 v[104:107], v[148:151], v[172:175], v[104:107]
	v_mfma_f32_16x16x32_bf16 v[100:103], v[156:159], v[172:175], v[100:103]
	v_mfma_f32_16x16x32_bf16 v[88:91], v[148:151], v[180:183], v[88:91]
	v_mfma_f32_16x16x32_bf16 v[84:87], v[156:159], v[180:183], v[84:87]
	v_mfma_f32_16x16x32_bf16 v[72:75], v[148:151], v[188:191], v[72:75]
	v_mfma_f32_16x16x32_bf16 v[68:71], v[156:159], v[188:191], v[68:71]
	v_mfma_f32_16x16x32_bf16 v[120:123], v[152:155], v[168:171], v[120:123]
	v_mfma_f32_16x16x32_bf16 v[116:119], v[160:163], v[168:171], v[116:119]
	v_mfma_f32_16x16x32_bf16 v[104:107], v[152:155], v[176:179], v[104:107]
	v_mfma_f32_16x16x32_bf16 v[100:103], v[160:163], v[176:179], v[100:103]
	v_mfma_f32_16x16x32_bf16 v[88:91], v[152:155], v[184:187], v[88:91]
	v_mfma_f32_16x16x32_bf16 v[84:87], v[160:163], v[184:187], v[84:87]
	v_mfma_f32_16x16x32_bf16 v[72:75], v[152:155], v[192:195], v[72:75]
	v_mfma_f32_16x16x32_bf16 v[68:71], v[160:163], v[192:195], v[68:71]
	s_barrier
	s_add_i32 s94, s94, s67
	v_lshl_add_u64 v[240:241], s[34:35], 0, v[212:213]
	s_mov_b32 m0, s94
	ds_read_b128 v[164:167], v209 offset:16384
	ds_read_b128 v[168:171], v209 offset:17408
	ds_read_b128 v[172:175], v209 offset:18432
	ds_read_b128 v[176:179], v209 offset:19456
	ds_read_b128 v[180:183], v209 offset:20480
	ds_read_b128 v[184:187], v209 offset:21504
	ds_read_b128 v[188:191], v209 offset:22528
	ds_read_b128 v[192:195], v209 offset:23552
	global_load_lds_dwordx4 v[240:241], off
	s_add_i32 m0, s94, 0x2000
	s_add_u32 s94, s34, 0x80000
	v_lshl_add_u64 v[242:243], s[34:35], 0, v[216:217]
	s_addc_u32 s95, s35, 0
	s_add_i32 s96, s96, s67
	global_load_lds_dwordx4 v[242:243], off
	v_lshl_add_u64 v[2:3], s[94:95], 0, v[212:213]
	s_mov_b32 m0, s96
	v_lshl_add_u64 v[244:245], s[54:55], 0, v[210:211]
	global_load_lds_dwordx4 v[2:3], off
	v_lshl_add_u64 v[2:3], s[94:95], 0, v[216:217]
	s_add_i32 m0, s96, 0x2000
	v_lshl_add_u64 v[246:247], s[54:55], 0, v[214:215]
	global_load_lds_dwordx4 v[2:3], off
	s_waitcnt vmcnt(4)
	s_waitcnt lgkmcnt(0)
	s_barrier
; #define PG8_STAGE(bufoff, gbase, voff) do { _Pragma("unroll") for (int _i = 0; _i < 2; ++_i) \
;         __builtin_amdgcn_global_load_lds((const unsigned*)((const char*)(gbase) + (voff)[_i]), (LAS unsigned*)(lds + (bufoff) + ldsw + _i * 8192), 16, 0, 0); } while (0)
; #define PG8_LDA(dst, b, h) do { _Pragma("unroll") for (int m = 0; m < 4; ++m) _Pragma("unroll") for (int k = 0; k < 2; ++k) dst[m][k] = *(const LAS bf16x8*)(lds + PG8_SA(b, h) + aoff + m * 2048 + k * 1024); } while (0)
; #define PG8_LDB(dst, b, h) do { _Pragma("unroll") for (int n = 0; n < 2; ++n) _Pragma("unroll") for (int k = 0; k < 2; ++k) dst[n][k] = *(const LAS bf16x8*)(lds + PG8_SB(b, h) + boff + n * 2048 + k * 1024); } while (0)
; #define PG8_MMA(ai, bj, At, Bt) do { __builtin_amdgcn_s_setprio(1); _Pragma("unroll") for (int m = 0; m < 4; ++m) _Pragma("unroll") for (int n = 0; n < 2; ++n) _Pragma("unroll") for (int k = 0; k < 2; ++k) \
;         acc[ai][bj][m][n] = __builtin_amdgcn_mfma_f32_16x16x32_bf16(Bt[n][k], At[m][k], acc[ai][bj][m][n], 0, 0, 0); __builtin_amdgcn_s_setprio(0); } while (0)
; #define PG8_WAIT_V(n) asm volatile("s_waitcnt vmcnt(" #n ")" ::: "memory")
; #define PG8_WAIT_L(n) asm volatile("s_waitcnt lgkmcnt(" #n ")" ::: "memory")
; #define PG8_BAR __builtin_amdgcn_s_barrier()
; #define PG8_SCHED __builtin_amdgcn_sched_barrier(0)
; template <class Epi, bool ALIGN_EPI>
; __device__ __forceinline__ void gemm_phase(LAS unsigned char* lds, const int tid, const Gemm g, const StaticOrder& S, const Epi& E) {
;     ...
;             PG8_WAIT_V(8); PG8_WAIT_L(0); PG8_BAR; PG8_MMA(1, 0, At, B0); PG8_MMA(1, 1, At, B1); PG8_BAR; PG8_SCHED;
;             PG8_LDB(B0, 1, 0); PG8_LDB(B1, 1, 1); PG8_SCHED; PG8_LDA(At, 1, 0); PG8_STAGE(PG8_SA(0, 1), a2 + hstepA, voffA);
;             PG8_WAIT_V(8); PG8_WAIT_L(0); PG8_BAR; PG8_MMA(0, 0, At, B0); PG8_MMA(0, 1, At, B1); PG8_BAR; PG8_SCHED;
	v_mfma_f32_16x16x32_bf16 v[64:67], v[132:135], v[164:167], v[64:67]
	v_mfma_f32_16x16x32_bf16 v[60:63], v[140:143], v[164:167], v[60:63]
	v_mfma_f32_16x16x32_bf16 v[48:51], v[132:135], v[172:175], v[48:51]
	v_mfma_f32_16x16x32_bf16 v[44:47], v[140:143], v[172:175], v[44:47]
	v_mfma_f32_16x16x32_bf16 v[32:35], v[132:135], v[180:183], v[32:35]
	v_mfma_f32_16x16x32_bf16 v[28:31], v[140:143], v[180:183], v[28:31]
	v_mfma_f32_16x16x32_bf16 v[16:19], v[132:135], v[188:191], v[16:19]
	v_mfma_f32_16x16x32_bf16 v[12:15], v[140:143], v[188:191], v[12:15]
	v_mfma_f32_16x16x32_bf16 v[64:67], v[136:139], v[168:171], v[64:67]
	v_mfma_f32_16x16x32_bf16 v[60:63], v[144:147], v[168:171], v[60:63]
	v_mfma_f32_16x16x32_bf16 v[48:51], v[136:139], v[176:179], v[48:51]
	v_mfma_f32_16x16x32_bf16 v[44:47], v[144:147], v[176:179], v[44:47]
	v_mfma_f32_16x16x32_bf16 v[32:35], v[136:139], v[184:187], v[32:35]
	v_mfma_f32_16x16x32_bf16 v[28:31], v[144:147], v[184:187], v[28:31]
	v_mfma_f32_16x16x32_bf16 v[16:19], v[136:139], v[192:195], v[16:19]
	v_mfma_f32_16x16x32_bf16 v[12:15], v[144:147], v[192:195], v[12:15]
	v_mfma_f32_16x16x32_bf16 v[56:59], v[148:151], v[164:167], v[56:59]
	v_mfma_f32_16x16x32_bf16 v[52:55], v[156:159], v[164:167], v[52:55]
	v_mfma_f32_16x16x32_bf16 v[40:43], v[148:151], v[172:175], v[40:43]
	v_mfma_f32_16x16x32_bf16 v[36:39], v[156:159], v[172:175], v[36:39]
	v_mfma_f32_16x16x32_bf16 v[24:27], v[148:151], v[180:183], v[24:27]
	v_mfma_f32_16x16x32_bf16 v[20:23], v[156:159], v[180:183], v[20:23]
	v_mfma_f32_16x16x32_bf16 v[8:11], v[148:151], v[188:191], v[8:11]
	v_mfma_f32_16x16x32_bf16 v[2:5], v[156:159], v[188:191], v[4:7]
	v_mfma_f32_16x16x32_bf16 v[56:59], v[152:155], v[168:171], v[56:59]
	v_mfma_f32_16x16x32_bf16 v[52:55], v[160:163], v[168:171], v[52:55]
	v_mfma_f32_16x16x32_bf16 v[40:43], v[152:155], v[176:179], v[40:43]
	v_mfma_f32_16x16x32_bf16 v[36:39], v[160:163], v[176:179], v[36:39]
	v_mfma_f32_16x16x32_bf16 v[24:27], v[152:155], v[184:187], v[24:27]
	v_mfma_f32_16x16x32_bf16 v[20:23], v[160:163], v[184:187], v[20:23]
	v_mfma_f32_16x16x32_bf16 v[8:11], v[152:155], v[192:195], v[8:11]
	v_mfma_f32_16x16x32_bf16 v[2:5], v[160:163], v[192:195], v[2:5]
	s_barrier
	s_add_i32 s94, 0, 0x18000
	v_add_u32_e32 v0, s94, v205
	s_add_i32 s95, 0, 0x1c000
	ds_read_b128 v[132:135], v0
	ds_read_b128 v[136:139], v0 offset:1024
	ds_read_b128 v[140:143], v0 offset:2048
	ds_read_b128 v[144:147], v0 offset:3072
	v_add_u32_e32 v0, s95, v205
	ds_read_b128 v[148:151], v0
	ds_read_b128 v[152:155], v0 offset:1024
	ds_read_b128 v[156:159], v0 offset:2048
	ds_read_b128 v[160:163], v0 offset:3072
	s_mov_b32 m0, s68
	s_nop 0
	global_load_lds_dwordx4 v[244:245], off
	s_mov_b32 m0, s69
	s_nop 0
	global_load_lds_dwordx4 v[246:247], off
	s_add_u32 s54, s54, 0x80000
	s_addc_u32 s55, s55, 0
	s_mov_b32 m0, s70
	v_lshl_add_u64 v[6:7], s[54:55], 0, v[210:211]
	ds_read_b128 v[164:167], v209 offset:32768
	ds_read_b128 v[168:171], v209 offset:33792
	ds_read_b128 v[172:175], v209 offset:34816
	ds_read_b128 v[176:179], v209 offset:35840
	ds_read_b128 v[180:183], v209 offset:36864
	ds_read_b128 v[184:187], v209 offset:37888
	ds_read_b128 v[188:191], v209 offset:38912
	ds_read_b128 v[192:195], v209 offset:39936
	global_load_lds_dwordx4 v[6:7], off
	v_lshl_add_u64 v[6:7], s[54:55], 0, v[214:215]
	s_mov_b32 m0, s71
	s_nop 0
	global_load_lds_dwordx4 v[6:7], off
	s_waitcnt vmcnt(8)
	s_waitcnt lgkmcnt(0)
	s_barrier
; #define PG8_STAGE(bufoff, gbase, voff) do { _Pragma("unroll") for (int _i = 0; _i < 2; ++_i) \
;         __builtin_amdgcn_global_load_lds((const unsigned*)((const char*)(gbase) + (voff)[_i]), (LAS unsigned*)(lds + (bufoff) + ldsw + _i * 8192), 16, 0, 0); } while (0)
; #define PG8_LDA(dst, b, h) do { _Pragma("unroll") for (int m = 0; m < 4; ++m) _Pragma("unroll") for (int k = 0; k < 2; ++k) dst[m][k] = *(const LAS bf16x8*)(lds + PG8_SA(b, h) + aoff + m * 2048 + k * 1024); } while (0)
; #define PG8_MMA(ai, bj, At, Bt) do { __builtin_amdgcn_s_setprio(1); _Pragma("unroll") for (int m = 0; m < 4; ++m) _Pragma("unroll") for (int n = 0; n < 2; ++n) _Pragma("unroll") for (int k = 0; k < 2; ++k) \
;         acc[ai][bj][m][n] = __builtin_amdgcn_mfma_f32_16x16x32_bf16(Bt[n][k], At[m][k], acc[ai][bj][m][n], 0, 0, 0); __builtin_amdgcn_s_setprio(0); } while (0)
; #define PG8_WAIT_V(n) asm volatile("s_waitcnt vmcnt(" #n ")" ::: "memory")
; #define PG8_WAIT_L(n) asm volatile("s_waitcnt lgkmcnt(" #n ")" ::: "memory")
; #define PG8_BAR __builtin_amdgcn_s_barrier()
; #define PG8_SCHED __builtin_amdgcn_sched_barrier(0)
; template <class Epi, bool ALIGN_EPI>
; __device__ __forceinline__ void gemm_phase(LAS unsigned char* lds, const int tid, const Gemm g, const StaticOrder& S, const Epi& E) {
;     ...
;             PG8_WAIT_V(8); PG8_WAIT_L(0); PG8_BAR; PG8_MMA(0, 0, At, B0); PG8_MMA(0, 1, At, B1); PG8_BAR; PG8_SCHED;
;             PG8_LDA(At, 1, 1); PG8_STAGE(PG8_SB(1, 0), b3, voffB); PG8_STAGE(PG8_SB(1, 1), b3 + hstepB, voffB); PG8_STAGE(PG8_SA(1, 0), a3, voffA);
;             PG8_WAIT_V(8); PG8_WAIT_L(0); PG8_BAR; PG8_MMA(1, 0, At, B0); PG8_MMA(1, 1, At, B1); PG8_BAR; PG8_SCHED;
;         }
	v_mfma_f32_16x16x32_bf16 v[128:131], v[132:135], v[164:167], v[128:131]
	v_mfma_f32_16x16x32_bf16 v[124:127], v[140:143], v[164:167], v[124:127]
	v_mfma_f32_16x16x32_bf16 v[112:115], v[132:135], v[172:175], v[112:115]
	v_mfma_f32_16x16x32_bf16 v[108:111], v[140:143], v[172:175], v[108:111]
	v_mfma_f32_16x16x32_bf16 v[96:99], v[132:135], v[180:183], v[96:99]
	v_mfma_f32_16x16x32_bf16 v[92:95], v[140:143], v[180:183], v[92:95]
	v_mfma_f32_16x16x32_bf16 v[80:83], v[132:135], v[188:191], v[80:83]
	v_mfma_f32_16x16x32_bf16 v[76:79], v[140:143], v[188:191], v[76:79]
	v_mfma_f32_16x16x32_bf16 v[128:131], v[136:139], v[168:171], v[128:131]
	v_mfma_f32_16x16x32_bf16 v[124:127], v[144:147], v[168:171], v[124:127]
	v_mfma_f32_16x16x32_bf16 v[112:115], v[136:139], v[176:179], v[112:115]
	v_mfma_f32_16x16x32_bf16 v[108:111], v[144:147], v[176:179], v[108:111]
	v_mfma_f32_16x16x32_bf16 v[96:99], v[136:139], v[184:187], v[96:99]
	v_mfma_f32_16x16x32_bf16 v[92:95], v[144:147], v[184:187], v[92:95]
	v_mfma_f32_16x16x32_bf16 v[80:83], v[136:139], v[192:195], v[80:83]
	v_mfma_f32_16x16x32_bf16 v[76:79], v[144:147], v[192:195], v[76:79]
	v_mfma_f32_16x16x32_bf16 v[120:123], v[148:151], v[164:167], v[120:123]
	v_mfma_f32_16x16x32_bf16 v[116:119], v[156:159], v[164:167], v[116:119]
	v_mfma_f32_16x16x32_bf16 v[104:107], v[148:151], v[172:175], v[104:107]
	v_mfma_f32_16x16x32_bf16 v[100:103], v[156:159], v[172:175], v[100:103]
	v_mfma_f32_16x16x32_bf16 v[88:91], v[148:151], v[180:183], v[88:91]
	v_mfma_f32_16x16x32_bf16 v[84:87], v[156:159], v[180:183], v[84:87]
	v_mfma_f32_16x16x32_bf16 v[72:75], v[148:151], v[188:191], v[72:75]
	v_mfma_f32_16x16x32_bf16 v[68:71], v[156:159], v[188:191], v[68:71]
	v_mfma_f32_16x16x32_bf16 v[120:123], v[152:155], v[168:171], v[120:123]
	v_mfma_f32_16x16x32_bf16 v[116:119], v[160:163], v[168:171], v[116:119]
	v_mfma_f32_16x16x32_bf16 v[104:107], v[152:155], v[176:179], v[104:107]
	v_mfma_f32_16x16x32_bf16 v[100:103], v[160:163], v[176:179], v[100:103]
	v_mfma_f32_16x16x32_bf16 v[88:91], v[152:155], v[184:187], v[88:91]
	v_mfma_f32_16x16x32_bf16 v[84:87], v[160:163], v[184:187], v[84:87]
	v_mfma_f32_16x16x32_bf16 v[72:75], v[152:155], v[192:195], v[72:75]
	v_mfma_f32_16x16x32_bf16 v[68:71], v[160:163], v[192:195], v[68:71]
	s_barrier
	s_add_i32 s54, s94, s67
	v_lshl_add_u64 v[6:7], v[240:241], 0, s[42:43]
	s_mov_b32 m0, s54
	ds_read_b128 v[164:167], v209 offset:49152
	ds_read_b128 v[168:171], v209 offset:50176
	ds_read_b128 v[172:175], v209 offset:51200
	ds_read_b128 v[176:179], v209 offset:52224
	ds_read_b128 v[180:183], v209 offset:53248
	ds_read_b128 v[184:187], v209 offset:54272
	ds_read_b128 v[188:191], v209 offset:55296
	ds_read_b128 v[192:195], v209 offset:56320
	global_load_lds_dwordx4 v[6:7], off
	s_add_i32 m0, s54, 0x2000
	s_add_u32 s34, s34, 0x80080
	v_lshl_add_u64 v[6:7], v[242:243], 0, s[42:43]
	s_addc_u32 s35, s35, 0
	s_add_i32 s54, s95, s67
	global_load_lds_dwordx4 v[6:7], off
	v_lshl_add_u64 v[6:7], s[34:35], 0, v[212:213]
	s_mov_b32 m0, s54
	s_nop 0
	global_load_lds_dwordx4 v[6:7], off
	v_lshl_add_u64 v[6:7], s[34:35], 0, v[216:217]
	s_add_i32 m0, s54, 0x2000
	s_nop 0
	global_load_lds_dwordx4 v[6:7], off
	s_waitcnt vmcnt(4)
	s_waitcnt lgkmcnt(0)
	s_barrier
	v_mfma_f32_16x16x32_bf16 v[64:67], v[132:135], v[164:167], v[64:67]
	v_mfma_f32_16x16x32_bf16 v[60:63], v[140:143], v[164:167], v[60:63]
	v_mfma_f32_16x16x32_bf16 v[48:51], v[132:135], v[172:175], v[48:51]
	v_mfma_f32_16x16x32_bf16 v[44:47], v[140:143], v[172:175], v[44:47]
	v_mfma_f32_16x16x32_bf16 v[32:35], v[132:135], v[180:183], v[32:35]
	v_mfma_f32_16x16x32_bf16 v[28:31], v[140:143], v[180:183], v[28:31]
	v_mfma_f32_16x16x32_bf16 v[16:19], v[132:135], v[188:191], v[16:19]
	v_mfma_f32_16x16x32_bf16 v[12:15], v[140:143], v[188:191], v[12:15]
	v_mfma_f32_16x16x32_bf16 v[64:67], v[136:139], v[168:171], v[64:67]
	v_mfma_f32_16x16x32_bf16 v[60:63], v[144:147], v[168:171], v[60:63]
	v_mfma_f32_16x16x32_bf16 v[48:51], v[136:139], v[176:179], v[48:51]
	v_mfma_f32_16x16x32_bf16 v[44:47], v[144:147], v[176:179], v[44:47]
	v_mfma_f32_16x16x32_bf16 v[32:35], v[136:139], v[184:187], v[32:35]
	v_mfma_f32_16x16x32_bf16 v[28:31], v[144:147], v[184:187], v[28:31]
	v_mfma_f32_16x16x32_bf16 v[16:19], v[136:139], v[192:195], v[16:19]
	v_mfma_f32_16x16x32_bf16 v[12:15], v[144:147], v[192:195], v[12:15]
	v_mfma_f32_16x16x32_bf16 v[56:59], v[148:151], v[164:167], v[56:59]
	v_mfma_f32_16x16x32_bf16 v[52:55], v[156:159], v[164:167], v[52:55]
	v_mfma_f32_16x16x32_bf16 v[40:43], v[148:151], v[172:175], v[40:43]
	v_mfma_f32_16x16x32_bf16 v[36:39], v[156:159], v[172:175], v[36:39]
	v_mfma_f32_16x16x32_bf16 v[24:27], v[148:151], v[180:183], v[24:27]
	v_mfma_f32_16x16x32_bf16 v[20:23], v[156:159], v[180:183], v[20:23]
	v_mfma_f32_16x16x32_bf16 v[6:9], v[148:151], v[188:191], v[8:11]
	v_mfma_f32_16x16x32_bf16 v[2:5], v[156:159], v[188:191], v[2:5]
	v_mfma_f32_16x16x32_bf16 v[56:59], v[152:155], v[168:171], v[56:59]
	v_mfma_f32_16x16x32_bf16 v[52:55], v[160:163], v[168:171], v[52:55]
	v_mfma_f32_16x16x32_bf16 v[40:43], v[152:155], v[176:179], v[40:43]
	v_mfma_f32_16x16x32_bf16 v[36:39], v[160:163], v[176:179], v[36:39]
	v_mfma_f32_16x16x32_bf16 v[24:27], v[152:155], v[184:187], v[24:27]
	v_mfma_f32_16x16x32_bf16 v[20:23], v[160:163], v[184:187], v[20:23]
	v_mfma_f32_16x16x32_bf16 v[8:11], v[152:155], v[192:195], v[6:9]
	v_mfma_f32_16x16x32_bf16 v[4:7], v[160:163], v[192:195], v[2:5]
	s_barrier
	s_add_u32 s92, s92, 0x400
	s_addc_u32 s93, s93, 0
	s_add_u32 s21, s21, 0x100
	s_addc_u32 s36, s36, 0
	s_add_u32 s30, s30, 0x100
	s_addc_u32 s31, s31, 0
	s_cmp_ge_u32 s5, s19
	s_cbranch_scc1 .LBB0_266

; #define PG8_STAGE(bufoff, gbase, voff) do { _Pragma("unroll") for (int _i = 0; _i < 2; ++_i) \
;         __builtin_amdgcn_global_load_lds((const unsigned*)((const char*)(gbase) + (voff)[_i]), (LAS unsigned*)(lds + (bufoff) + ldsw + _i * 8192), 16, 0, 0); } while (0)
; #define PG8_LDA(dst, b, h) do { _Pragma("unroll") for (int m = 0; m < 4; ++m) _Pragma("unroll") for (int k = 0; k < 2; ++k) dst[m][k] = *(const LAS bf16x8*)(lds + PG8_SA(b, h) + aoff + m * 2048 + k * 1024); } while (0)
; #define PG8_LDB(dst, b, h) do { _Pragma("unroll") for (int n = 0; n < 2; ++n) _Pragma("unroll") for (int k = 0; k < 2; ++k) dst[n][k] = *(const LAS bf16x8*)(lds + PG8_SB(b, h) + boff + n * 2048 + k * 1024); } while (0)
; #define PG8_WAIT_V(n) asm volatile("s_waitcnt vmcnt(" #n ")" ::: "memory")
; #define PG8_WAIT_L(n) asm volatile("s_waitcnt lgkmcnt(" #n ")" ::: "memory")
; #define PG8_BAR __builtin_amdgcn_s_barrier()
; template <class Epi, bool ALIGN_EPI>
; __device__ __forceinline__ void gemm_phase(LAS unsigned char* lds, const int tid, const Gemm g, const StaticOrder& S, const Epi& E) {
;     ...
;         const bool has_next = S.next(ui + 1, nxt);
;         const char* nA = has_next ? (const char*)g.A + (size_t)nxt.pm * tstepA + PG8_KOFFA(nxt) : cA; const char* nB = has_next ? (const char*)g.Bt + (size_t)nxt.pn * tstepB + PG8_KOFFB(nxt) : cB;
;         const int nt = cur.ks >= 0 ? nt_split : nt_full;
;         for (int t = 0; t < nt; t += 2) {
;             if constexpr (Epi::HOOK) { if (t != 0 && (t & 7) == 0) E.hook(acc, cur, (t >> 3) - 1, wr, wc, fr, fq); }
;             const bool last = (t == nt - 2);
;             const char* a1 = cA + (size_t)(t + 1) * kstepA;
;             const char* a2 = last ? nA : cA + (size_t)(t + 2) * kstepA; const char* b2 = last ? nB : cB + (size_t)(t + 2) * kstepB;
;             const char* a3 = a2 + kstepA; const char* b3 = b2 + kstepB;
;             PG8_LDB(B0, 0, 0); PG8_LDB(B1, 0, 1); PG8_SCHED; PG8_LDA(At, 0, 0); PG8_STAGE(PG8_SA(1, 1), a1 + hstepA, voffA);
;             PG8_WAIT_V(8); PG8_WAIT_L(0); PG8_BAR; PG8_MMA(0, 0, At, B0); PG8_MMA(0, 1, At, B1); PG8_BAR; PG8_SCHED;
;             PG8_LDA(At, 0, 1); PG8_STAGE(PG8_SB(0, 0), b2, voffB); PG8_STAGE(PG8_SB(0, 1), b2 + hstepB, voffB); PG8_STAGE(PG8_SA(0, 0), a2, voffA);
;             PG8_WAIT_V(8); PG8_WAIT_L(0); PG8_BAR; PG8_MMA(1, 0, At, B0); PG8_MMA(1, 1, At, B1); PG8_BAR; PG8_SCHED;
.LBB0_667:
	s_setprio 0
	s_add_u32 s22, s20, 0xfff80080
	s_addc_u32 s23, s21, -1
	s_add_i32 s49, 0, 0x10000
	s_cmp_eq_u32 s19, 28
	s_cselect_b32 s25, s15, s23
	s_cselect_b32 s24, s14, s22
	v_add_u32_e32 v0, s49, v173
	s_cselect_b32 s23, s17, s13
	s_cselect_b32 s22, s16, s11
	s_add_i32 s52, 0, 0x14000
	ds_read_b128 v[130:133], v0
	ds_read_b128 v[134:137], v0 offset:1024
	ds_read_b128 v[138:141], v0 offset:2048
	ds_read_b128 v[142:145], v0 offset:3072
	v_add_u32_e32 v0, s52, v173
	ds_read_b128 v[158:161], v0
	ds_read_b128 v[162:165], v0 offset:1024
	ds_read_b128 v[166:169], v0 offset:2048
	ds_read_b128 v[178:181], v0 offset:3072
	v_lshl_add_u64 v[170:171], s[20:21], 0, v[156:157]
	s_add_i32 m0, s28, 0xc000
	ds_read_b128 v[182:185], v176
	ds_read_b128 v[186:189], v176 offset:1024
	ds_read_b128 v[190:193], v176 offset:2048
	ds_read_b128 v[208:211], v176 offset:3072
	ds_read_b128 v[212:215], v176 offset:4096
	ds_read_b128 v[216:219], v176 offset:5120
	ds_read_b128 v[220:223], v176 offset:6144
	ds_read_b128 v[240:243], v176 offset:7168
	global_load_lds_dwordx4 v[170:171], off
	v_lshl_add_u64 v[170:171], s[20:21], 0, v[154:155]
	s_add_i32 m0, s28, 0xe000
	s_nop 0
	global_load_lds_dwordx4 v[170:171], off
	s_sub_u32 s98, s20, 0x80000
	s_subb_u32 s99, s21, 0
	v_lshl_add_u64 v[170:171], s[98:99], 0, v[156:157]
	s_mov_b32 m0, s34
	s_nop 0
	global_load_lds_dwordx4 v[170:171], off
	v_lshl_add_u64 v[170:171], s[98:99], 0, v[154:155]
	s_mov_b32 m0, s35
	s_nop 0
	global_load_lds_dwordx4 v[170:171], off
	s_waitcnt vmcnt(8)
	s_waitcnt lgkmcnt(0)
	s_barrier
	v_mfma_f32_16x16x32_bf16 v[126:129], v[130:133], v[182:185], v[126:129]
	v_mfma_f32_16x16x32_bf16 v[122:125], v[138:141], v[182:185], v[122:125]
	v_mfma_f32_16x16x32_bf16 v[118:121], v[130:133], v[190:193], v[118:121]
	v_mfma_f32_16x16x32_bf16 v[114:117], v[138:141], v[190:193], v[114:117]
	v_mfma_f32_16x16x32_bf16 v[102:105], v[130:133], v[212:215], v[102:105]
	v_mfma_f32_16x16x32_bf16 v[98:101], v[138:141], v[212:215], v[98:101]
	v_mfma_f32_16x16x32_bf16 v[86:89], v[130:133], v[220:223], v[86:89]
	v_mfma_f32_16x16x32_bf16 v[82:85], v[138:141], v[220:223], v[82:85]
	v_mfma_f32_16x16x32_bf16 v[126:129], v[134:137], v[186:189], v[126:129]
	v_mfma_f32_16x16x32_bf16 v[122:125], v[142:145], v[186:189], v[122:125]
	v_mfma_f32_16x16x32_bf16 v[118:121], v[134:137], v[208:211], v[118:121]
	v_mfma_f32_16x16x32_bf16 v[114:117], v[142:145], v[208:211], v[114:117]
	v_mfma_f32_16x16x32_bf16 v[102:105], v[134:137], v[216:219], v[102:105]
	v_mfma_f32_16x16x32_bf16 v[98:101], v[142:145], v[216:219], v[98:101]
	v_mfma_f32_16x16x32_bf16 v[86:89], v[134:137], v[240:243], v[86:89]
	v_mfma_f32_16x16x32_bf16 v[82:85], v[142:145], v[240:243], v[82:85]
	v_mfma_f32_16x16x32_bf16 v[110:113], v[158:161], v[182:185], v[110:113]
	v_mfma_f32_16x16x32_bf16 v[106:109], v[166:169], v[182:185], v[106:109]
	v_mfma_f32_16x16x32_bf16 v[94:97], v[158:161], v[190:193], v[94:97]
	v_mfma_f32_16x16x32_bf16 v[90:93], v[166:169], v[190:193], v[90:93]
	v_mfma_f32_16x16x32_bf16 v[78:81], v[158:161], v[212:215], v[78:81]
	v_mfma_f32_16x16x32_bf16 v[74:77], v[166:169], v[212:215], v[74:77]
	v_mfma_f32_16x16x32_bf16 v[70:73], v[158:161], v[220:223], v[70:73]
	v_mfma_f32_16x16x32_bf16 v[66:69], v[166:169], v[220:223], v[66:69]
	v_mfma_f32_16x16x32_bf16 v[110:113], v[162:165], v[186:189], v[110:113]
	v_mfma_f32_16x16x32_bf16 v[106:109], v[178:181], v[186:189], v[106:109]
	v_mfma_f32_16x16x32_bf16 v[94:97], v[162:165], v[208:211], v[94:97]
	v_mfma_f32_16x16x32_bf16 v[90:93], v[178:181], v[208:211], v[90:93]
	v_mfma_f32_16x16x32_bf16 v[78:81], v[162:165], v[216:219], v[78:81]
	v_mfma_f32_16x16x32_bf16 v[74:77], v[178:181], v[216:219], v[74:77]
	v_mfma_f32_16x16x32_bf16 v[70:73], v[162:165], v[240:243], v[70:73]
	v_mfma_f32_16x16x32_bf16 v[66:69], v[178:181], v[240:243], v[66:69]
	s_barrier
	s_add_i32 s49, s49, s27
	v_lshl_add_u64 v[170:171], s[22:23], 0, v[148:149]
	s_mov_b32 m0, s49
	ds_read_b128 v[182:185], v176 offset:16384
	ds_read_b128 v[186:189], v176 offset:17408
	ds_read_b128 v[190:193], v176 offset:18432
	ds_read_b128 v[208:211], v176 offset:19456
	ds_read_b128 v[212:215], v176 offset:20480
	ds_read_b128 v[216:219], v176 offset:21504
	ds_read_b128 v[220:223], v176 offset:22528
	ds_read_b128 v[240:243], v176 offset:23552
	global_load_lds_dwordx4 v[170:171], off
	s_add_i32 m0, s49, 0x2000
	s_add_u32 s54, s22, 0x80000
	v_lshl_add_u64 v[194:195], s[22:23], 0, v[152:153]
	s_addc_u32 s55, s23, 0
	s_add_i32 s49, s52, s27
	global_load_lds_dwordx4 v[194:195], off
	v_lshl_add_u64 v[224:225], s[54:55], 0, v[148:149]
	s_mov_b32 m0, s49
	v_lshl_add_u64 v[244:245], s[24:25], 0, v[150:151]
	global_load_lds_dwordx4 v[224:225], off
	v_lshl_add_u64 v[224:225], s[54:55], 0, v[152:153]
	s_add_i32 m0, s49, 0x2000
	s_nop 0
	global_load_lds_dwordx4 v[224:225], off
	v_lshl_add_u64 v[224:225], s[24:25], 0, v[146:147]
	s_waitcnt vmcnt(4)
	s_waitcnt lgkmcnt(0)
	s_barrier
; #define PG8_STAGE(bufoff, gbase, voff) do { _Pragma("unroll") for (int _i = 0; _i < 2; ++_i) \
;         __builtin_amdgcn_global_load_lds((const unsigned*)((const char*)(gbase) + (voff)[_i]), (LAS unsigned*)(lds + (bufoff) + ldsw + _i * 8192), 16, 0, 0); } while (0)
; #define PG8_LDA(dst, b, h) do { _Pragma("unroll") for (int m = 0; m < 4; ++m) _Pragma("unroll") for (int k = 0; k < 2; ++k) dst[m][k] = *(const LAS bf16x8*)(lds + PG8_SA(b, h) + aoff + m * 2048 + k * 1024); } while (0)
; #define PG8_LDB(dst, b, h) do { _Pragma("unroll") for (int n = 0; n < 2; ++n) _Pragma("unroll") for (int k = 0; k < 2; ++k) dst[n][k] = *(const LAS bf16x8*)(lds + PG8_SB(b, h) + boff + n * 2048 + k * 1024); } while (0)
; #define PG8_MMA(ai, bj, At, Bt) do { __builtin_amdgcn_s_setprio(1); _Pragma("unroll") for (int m = 0; m < 4; ++m) _Pragma("unroll") for (int n = 0; n < 2; ++n) _Pragma("unroll") for (int k = 0; k < 2; ++k) \
;         acc[ai][bj][m][n] = __builtin_amdgcn_mfma_f32_16x16x32_bf16(Bt[n][k], At[m][k], acc[ai][bj][m][n], 0, 0, 0); __builtin_amdgcn_s_setprio(0); } while (0)
; #define PG8_WAIT_V(n) asm volatile("s_waitcnt vmcnt(" #n ")" ::: "memory")
; #define PG8_WAIT_L(n) asm volatile("s_waitcnt lgkmcnt(" #n ")" ::: "memory")
; #define PG8_BAR __builtin_amdgcn_s_barrier()
; #define PG8_SCHED __builtin_amdgcn_sched_barrier(0)
; template <class Epi, bool ALIGN_EPI>
; __device__ __forceinline__ void gemm_phase(LAS unsigned char* lds, const int tid, const Gemm g, const StaticOrder& S, const Epi& E) {
;     ...
;             PG8_WAIT_V(8); PG8_WAIT_L(0); PG8_BAR; PG8_MMA(1, 0, At, B0); PG8_MMA(1, 1, At, B1); PG8_BAR; PG8_SCHED;
;             PG8_LDB(B0, 1, 0); PG8_LDB(B1, 1, 1); PG8_SCHED; PG8_LDA(At, 1, 0); PG8_STAGE(PG8_SA(0, 1), a2 + hstepA, voffA);
;             PG8_WAIT_V(8); PG8_WAIT_L(0); PG8_BAR; PG8_MMA(0, 0, At, B0); PG8_MMA(0, 1, At, B1); PG8_BAR; PG8_SCHED;
	v_mfma_f32_16x16x32_bf16 v[62:65], v[130:133], v[182:185], v[62:65]
	v_mfma_f32_16x16x32_bf16 v[58:61], v[138:141], v[182:185], v[58:61]
	v_mfma_f32_16x16x32_bf16 v[54:57], v[130:133], v[190:193], v[54:57]
	v_mfma_f32_16x16x32_bf16 v[50:53], v[138:141], v[190:193], v[50:53]
	v_mfma_f32_16x16x32_bf16 v[38:41], v[130:133], v[212:215], v[38:41]
	v_mfma_f32_16x16x32_bf16 v[34:37], v[138:141], v[212:215], v[34:37]
	v_mfma_f32_16x16x32_bf16 v[22:25], v[130:133], v[220:223], v[22:25]
	v_mfma_f32_16x16x32_bf16 v[18:21], v[138:141], v[220:223], v[18:21]
	v_mfma_f32_16x16x32_bf16 v[62:65], v[134:137], v[186:189], v[62:65]
	v_mfma_f32_16x16x32_bf16 v[58:61], v[142:145], v[186:189], v[58:61]
	v_mfma_f32_16x16x32_bf16 v[54:57], v[134:137], v[208:211], v[54:57]
	v_mfma_f32_16x16x32_bf16 v[50:53], v[142:145], v[208:211], v[50:53]
	v_mfma_f32_16x16x32_bf16 v[38:41], v[134:137], v[216:219], v[38:41]
	v_mfma_f32_16x16x32_bf16 v[34:37], v[142:145], v[216:219], v[34:37]
	v_mfma_f32_16x16x32_bf16 v[22:25], v[134:137], v[240:243], v[22:25]
	v_mfma_f32_16x16x32_bf16 v[18:21], v[142:145], v[240:243], v[18:21]
	v_mfma_f32_16x16x32_bf16 v[46:49], v[158:161], v[182:185], v[46:49]
	v_mfma_f32_16x16x32_bf16 v[42:45], v[166:169], v[182:185], v[42:45]
	v_mfma_f32_16x16x32_bf16 v[30:33], v[158:161], v[190:193], v[30:33]
	v_mfma_f32_16x16x32_bf16 v[26:29], v[166:169], v[190:193], v[26:29]
	v_mfma_f32_16x16x32_bf16 v[14:17], v[158:161], v[212:215], v[14:17]
	v_mfma_f32_16x16x32_bf16 v[10:13], v[166:169], v[212:215], v[10:13]
	v_mfma_f32_16x16x32_bf16 v[6:9], v[158:161], v[220:223], v[6:9]
	v_mfma_f32_16x16x32_bf16 v[2:5], v[166:169], v[220:223], v[2:5]
	v_mfma_f32_16x16x32_bf16 v[46:49], v[162:165], v[186:189], v[46:49]
	v_mfma_f32_16x16x32_bf16 v[42:45], v[178:181], v[186:189], v[42:45]
	v_mfma_f32_16x16x32_bf16 v[30:33], v[162:165], v[208:211], v[30:33]
	v_mfma_f32_16x16x32_bf16 v[26:29], v[178:181], v[208:211], v[26:29]
	v_mfma_f32_16x16x32_bf16 v[14:17], v[162:165], v[216:219], v[14:17]
	v_mfma_f32_16x16x32_bf16 v[10:13], v[178:181], v[216:219], v[10:13]
	v_mfma_f32_16x16x32_bf16 v[6:9], v[162:165], v[240:243], v[6:9]
	v_mfma_f32_16x16x32_bf16 v[2:5], v[178:181], v[240:243], v[2:5]
	s_barrier
	s_add_i32 s49, 0, 0x18000
	v_add_u32_e32 v0, s49, v173
	s_add_i32 s52, 0, 0x1c000
	ds_read_b128 v[130:133], v0
	ds_read_b128 v[134:137], v0 offset:1024
	ds_read_b128 v[138:141], v0 offset:2048
	ds_read_b128 v[142:145], v0 offset:3072
	v_add_u32_e32 v0, s52, v173
	ds_read_b128 v[158:161], v0
	ds_read_b128 v[162:165], v0 offset:1024
	ds_read_b128 v[166:169], v0 offset:2048
	ds_read_b128 v[178:181], v0 offset:3072
	s_mov_b32 m0, s28
	s_nop 0
	global_load_lds_dwordx4 v[224:225], off
	s_mov_b32 m0, s29
	s_nop 0
	global_load_lds_dwordx4 v[244:245], off
	s_add_u32 s24, s24, 0x80000
	s_addc_u32 s25, s25, 0
	s_mov_b32 m0, s30
	v_lshl_add_u64 v[246:247], s[24:25], 0, v[146:147]
	ds_read_b128 v[182:185], v176 offset:32768
	ds_read_b128 v[186:189], v176 offset:33792
	ds_read_b128 v[190:193], v176 offset:34816
	ds_read_b128 v[208:211], v176 offset:35840
	ds_read_b128 v[212:215], v176 offset:36864
	ds_read_b128 v[216:219], v176 offset:37888
	ds_read_b128 v[220:223], v176 offset:38912
	ds_read_b128 v[240:243], v176 offset:39936
	global_load_lds_dwordx4 v[246:247], off
	v_lshl_add_u64 v[246:247], s[24:25], 0, v[150:151]
	s_mov_b32 m0, s31
	s_nop 0
	global_load_lds_dwordx4 v[246:247], off
	s_waitcnt vmcnt(8)
	s_waitcnt lgkmcnt(0)
	s_barrier
	v_mfma_f32_16x16x32_bf16 v[126:129], v[130:133], v[182:185], v[126:129]
	v_mfma_f32_16x16x32_bf16 v[122:125], v[138:141], v[182:185], v[122:125]
	v_mfma_f32_16x16x32_bf16 v[118:121], v[130:133], v[190:193], v[118:121]
	v_mfma_f32_16x16x32_bf16 v[114:117], v[138:141], v[190:193], v[114:117]
	v_mfma_f32_16x16x32_bf16 v[102:105], v[130:133], v[212:215], v[102:105]
	v_mfma_f32_16x16x32_bf16 v[98:101], v[138:141], v[212:215], v[98:101]
	v_mfma_f32_16x16x32_bf16 v[86:89], v[130:133], v[220:223], v[86:89]
	v_mfma_f32_16x16x32_bf16 v[82:85], v[138:141], v[220:223], v[82:85]
	v_mfma_f32_16x16x32_bf16 v[126:129], v[134:137], v[186:189], v[126:129]
	v_mfma_f32_16x16x32_bf16 v[122:125], v[142:145], v[186:189], v[122:125]
	v_mfma_f32_16x16x32_bf16 v[118:121], v[134:137], v[208:211], v[118:121]
	v_mfma_f32_16x16x32_bf16 v[114:117], v[142:145], v[208:211], v[114:117]
	v_mfma_f32_16x16x32_bf16 v[102:105], v[134:137], v[216:219], v[102:105]
	v_mfma_f32_16x16x32_bf16 v[98:101], v[142:145], v[216:219], v[98:101]
	v_mfma_f32_16x16x32_bf16 v[86:89], v[134:137], v[240:243], v[86:89]
	v_mfma_f32_16x16x32_bf16 v[82:85], v[142:145], v[240:243], v[82:85]
	v_mfma_f32_16x16x32_bf16 v[110:113], v[158:161], v[182:185], v[110:113]
	v_mfma_f32_16x16x32_bf16 v[106:109], v[166:169], v[182:185], v[106:109]
	v_mfma_f32_16x16x32_bf16 v[94:97], v[158:161], v[190:193], v[94:97]
	v_mfma_f32_16x16x32_bf16 v[90:93], v[166:169], v[190:193], v[90:93]
	v_mfma_f32_16x16x32_bf16 v[78:81], v[158:161], v[212:215], v[78:81]
	v_mfma_f32_16x16x32_bf16 v[74:77], v[166:169], v[212:215], v[74:77]
	v_mfma_f32_16x16x32_bf16 v[70:73], v[158:161], v[220:223], v[70:73]
	v_mfma_f32_16x16x32_bf16 v[66:69], v[166:169], v[220:223], v[66:69]
	v_mfma_f32_16x16x32_bf16 v[110:113], v[162:165], v[186:189], v[110:113]
	v_mfma_f32_16x16x32_bf16 v[106:109], v[178:181], v[186:189], v[106:109]
	v_mfma_f32_16x16x32_bf16 v[94:97], v[162:165], v[208:211], v[94:97]
	v_mfma_f32_16x16x32_bf16 v[90:93], v[178:181], v[208:211], v[90:93]
	v_mfma_f32_16x16x32_bf16 v[78:81], v[162:165], v[216:219], v[78:81]
	v_mfma_f32_16x16x32_bf16 v[74:77], v[178:181], v[216:219], v[74:77]
	v_mfma_f32_16x16x32_bf16 v[70:73], v[162:165], v[240:243], v[70:73]
	v_mfma_f32_16x16x32_bf16 v[66:69], v[178:181], v[240:243], v[66:69]
	s_barrier
; #define GAS __attribute__((address_space(1)))
; #define PG8_STAGE(bufoff, gbase, voff) do { _Pragma("unroll") for (int _i = 0; _i < 2; ++_i) \
;         __builtin_amdgcn_global_load_lds((const unsigned*)((const char*)(gbase) + (voff)[_i]), (LAS unsigned*)(lds + (bufoff) + ldsw + _i * 8192), 16, 0, 0); } while (0)
; #define PG8_LDA(dst, b, h) do { _Pragma("unroll") for (int m = 0; m < 4; ++m) _Pragma("unroll") for (int k = 0; k < 2; ++k) dst[m][k] = *(const LAS bf16x8*)(lds + PG8_SA(b, h) + aoff + m * 2048 + k * 1024); } while (0)
; #define PG8_MMA(ai, bj, At, Bt) do { __builtin_amdgcn_s_setprio(1); _Pragma("unroll") for (int m = 0; m < 4; ++m) _Pragma("unroll") for (int n = 0; n < 2; ++n) _Pragma("unroll") for (int k = 0; k < 2; ++k) \
;         acc[ai][bj][m][n] = __builtin_amdgcn_mfma_f32_16x16x32_bf16(Bt[n][k], At[m][k], acc[ai][bj][m][n], 0, 0, 0); __builtin_amdgcn_s_setprio(0); } while (0)
; #define PG8_WAIT_V(n) asm volatile("s_waitcnt vmcnt(" #n ")" ::: "memory")
; #define PG8_WAIT_L(n) asm volatile("s_waitcnt lgkmcnt(" #n ")" ::: "memory")
; #define PG8_BAR __builtin_amdgcn_s_barrier()
; #define PG8_SCHED __builtin_amdgcn_sched_barrier(0)
; template <class Epi, bool ALIGN_EPI>
; __device__ __forceinline__ void gemm_phase(LAS unsigned char* lds, const int tid, const Gemm g, const StaticOrder& S, const Epi& E) {
;     ...
;             PG8_LDA(At, 1, 1); PG8_STAGE(PG8_SB(1, 0), b3, voffB); PG8_STAGE(PG8_SB(1, 1), b3 + hstepB, voffB); PG8_STAGE(PG8_SA(1, 0), a3, voffA);
;             PG8_WAIT_V(8); PG8_WAIT_L(0); PG8_BAR; PG8_MMA(1, 0, At, B0); PG8_MMA(1, 1, At, B1); PG8_BAR; PG8_SCHED;
;         }
;         if constexpr (ALIGN_EPI) { if (wr == 0) PG8_BAR; }
;         E(acc, cur, wr, wc, fr, fq);
;     __device__ __forceinline__ void operator()(const f32x4 (&acc)[2][2][4][2], const Unit& u, int wr, int wc, int fr, int fq) const {
;     ...
;             const int col0 = colt - ZW + wc * 32 + 8 * fq;
;             f32x4 bv[2][2];
; #pragma unroll
;             for (int bj = 0; bj < 2; ++bj)
; #pragma unroll
;                 for (int n = 0; n < 2; ++n) bv[bj][n] = *(const GAS f32x4*)(bgate + col0 + bj * HALF + 4 * n);
	s_add_i32 s24, s49, s27
	v_lshl_add_u64 v[170:171], v[170:171], 0, s[42:43]
	s_mov_b32 m0, s24
	ds_read_b128 v[182:185], v176 offset:49152
	ds_read_b128 v[186:189], v176 offset:50176
	ds_read_b128 v[190:193], v176 offset:51200
	ds_read_b128 v[208:211], v176 offset:52224
	ds_read_b128 v[212:215], v176 offset:53248
	ds_read_b128 v[216:219], v176 offset:54272
	ds_read_b128 v[220:223], v176 offset:55296
	ds_read_b128 v[240:243], v176 offset:56320
	global_load_lds_dwordx4 v[170:171], off
	s_add_i32 m0, s24, 0x2000
	s_add_u32 s22, s22, 0x80080
	v_lshl_add_u64 v[170:171], v[194:195], 0, s[42:43]
	s_addc_u32 s23, s23, 0
	s_add_i32 s24, s52, s27
	global_load_lds_dwordx4 v[170:171], off
	v_lshl_add_u64 v[170:171], s[22:23], 0, v[148:149]
	s_mov_b32 m0, s24
	s_nop 0
	global_load_lds_dwordx4 v[170:171], off
	v_lshl_add_u64 v[170:171], s[22:23], 0, v[152:153]
	s_add_i32 m0, s24, 0x2000
	s_nop 0
	global_load_lds_dwordx4 v[170:171], off
	s_waitcnt vmcnt(4)
	s_waitcnt lgkmcnt(0)
	s_barrier
	v_mfma_f32_16x16x32_bf16 v[62:65], v[130:133], v[182:185], v[62:65]
	v_mfma_f32_16x16x32_bf16 v[58:61], v[138:141], v[182:185], v[58:61]
	v_mfma_f32_16x16x32_bf16 v[54:57], v[130:133], v[190:193], v[54:57]
	v_mfma_f32_16x16x32_bf16 v[50:53], v[138:141], v[190:193], v[50:53]
	v_mfma_f32_16x16x32_bf16 v[38:41], v[130:133], v[212:215], v[38:41]
	v_mfma_f32_16x16x32_bf16 v[34:37], v[138:141], v[212:215], v[34:37]
	v_mfma_f32_16x16x32_bf16 v[22:25], v[130:133], v[220:223], v[22:25]
	v_mfma_f32_16x16x32_bf16 v[18:21], v[138:141], v[220:223], v[18:21]
	v_mfma_f32_16x16x32_bf16 v[62:65], v[134:137], v[186:189], v[62:65]
	v_mfma_f32_16x16x32_bf16 v[58:61], v[142:145], v[186:189], v[58:61]
	v_mfma_f32_16x16x32_bf16 v[54:57], v[134:137], v[208:211], v[54:57]
	v_mfma_f32_16x16x32_bf16 v[50:53], v[142:145], v[208:211], v[50:53]
	v_mfma_f32_16x16x32_bf16 v[38:41], v[134:137], v[216:219], v[38:41]
	v_mfma_f32_16x16x32_bf16 v[34:37], v[142:145], v[216:219], v[34:37]
	v_mfma_f32_16x16x32_bf16 v[22:25], v[134:137], v[240:243], v[22:25]
	v_mfma_f32_16x16x32_bf16 v[18:21], v[142:145], v[240:243], v[18:21]
	v_mfma_f32_16x16x32_bf16 v[46:49], v[158:161], v[182:185], v[46:49]
	v_mfma_f32_16x16x32_bf16 v[42:45], v[166:169], v[182:185], v[42:45]
	v_mfma_f32_16x16x32_bf16 v[30:33], v[158:161], v[190:193], v[30:33]
	v_mfma_f32_16x16x32_bf16 v[26:29], v[166:169], v[190:193], v[26:29]
	v_mfma_f32_16x16x32_bf16 v[14:17], v[158:161], v[212:215], v[14:17]
	v_mfma_f32_16x16x32_bf16 v[10:13], v[166:169], v[212:215], v[10:13]
	v_mfma_f32_16x16x32_bf16 v[6:9], v[158:161], v[220:223], v[6:9]
	v_mfma_f32_16x16x32_bf16 v[2:5], v[166:169], v[220:223], v[2:5]
	v_mfma_f32_16x16x32_bf16 v[46:49], v[162:165], v[186:189], v[46:49]
	v_mfma_f32_16x16x32_bf16 v[42:45], v[178:181], v[186:189], v[42:45]
	v_mfma_f32_16x16x32_bf16 v[30:33], v[162:165], v[208:211], v[30:33]
	v_mfma_f32_16x16x32_bf16 v[26:29], v[178:181], v[208:211], v[26:29]
	v_mfma_f32_16x16x32_bf16 v[14:17], v[162:165], v[216:219], v[14:17]
	v_mfma_f32_16x16x32_bf16 v[10:13], v[178:181], v[216:219], v[10:13]
	v_mfma_f32_16x16x32_bf16 v[6:9], v[162:165], v[240:243], v[6:9]
	v_mfma_f32_16x16x32_bf16 v[2:5], v[178:181], v[240:243], v[2:5]
	s_barrier
	s_add_i32 s19, s19, 2
	s_add_u32 s11, s11, 0x100
	s_addc_u32 s13, s13, 0
	s_add_u32 s20, s20, 0x100
	s_addc_u32 s21, s21, 0
	s_cmp_gt_u32 s19, 29
	s_cbranch_scc0 .LBB0_667
	s_lshl_b32 s11, s41, 8
	s_cmp_gt_i32 s41, 16
	s_cbranch_scc0 .Lwin_nobias
	v_add_u32_e32 v0, s11, v175
	v_lshl_add_u64 v[134:135], v[0:1], 2, s[6:7]
	global_load_dwordx4 v[138:141], v[134:135], off offset:16
	global_load_dwordx4 v[142:145], v[134:135], off
	global_load_dwordx4 v[130:133], v[134:135], off offset:528
	s_nop 0
	global_load_dwordx4 v[134:137], v[134:135], off offset:512
.Lwin_nobias:
	s_and_b64 vcc, exec, s[8:9]
	s_cbranch_vccz .LBB0_670
	s_barrier
	s_setprio 1
